# all LDS-DMA loads in the four FFN K-loops use SGPR-base + 32-bit VGPR offset addressing (no 64-bit VALU address adds); +12 in other loops
# speedup vs baseline: 1.0170x; 1.0101x over previous
.LBB0_402:
	s_add_u32 s20, s18, 0xfffc0080
	s_addc_u32 s21, s19, -1
	s_add_i32 s41, 0, 0x10000
	v_add_u32_e32 v142, s41, v145
	ds_read_b128 v[138:141], v142
	ds_read_b128 v[148:151], v142 offset:1024
	ds_read_b128 v[152:155], v142 offset:2048
	ds_read_b128 v[156:159], v142 offset:3072
	s_cmp_eq_u32 s40, 12
	s_cselect_b32 s23, s1, s21
	s_cselect_b32 s22, s9, s20
	s_cselect_b32 s21, s11, s39
	s_cselect_b32 s20, s33, s38
	s_add_i32 m0, s17, 0xc000
	ds_read_b128 v[160:163], v146
	ds_read_b128 v[164:167], v146 offset:1024
	ds_read_b128 v[168:171], v146 offset:2048
	ds_read_b128 v[172:175], v146 offset:3072
	ds_read_b128 v[176:179], v146 offset:4096
	ds_read_b128 v[180:183], v146 offset:5120
	ds_read_b128 v[184:187], v146 offset:6144
	ds_read_b128 v[188:191], v146 offset:7168
	global_load_lds_dwordx4 v136, s[18:19]
	s_add_i32 m0, s17, 0xe000
	s_nop 0
	global_load_lds_dwordx4 v134, s[18:19]
	s_waitcnt lgkmcnt(8)
	s_barrier
	s_waitcnt lgkmcnt(0)
	s_setprio 1
	s_waitcnt lgkmcnt(0)
	v_mfma_f32_16x16x32_bf16 v[124:127], v[138:141], v[160:163], v[124:127]
	v_mfma_f32_16x16x32_bf16 v[116:119], v[152:155], v[160:163], v[116:119]
	v_mfma_f32_16x16x32_bf16 v[108:111], v[138:141], v[168:171], v[108:111]
	v_mfma_f32_16x16x32_bf16 v[100:103], v[152:155], v[168:171], v[100:103]
	v_mfma_f32_16x16x32_bf16 v[92:95], v[138:141], v[176:179], v[92:95]
	v_mfma_f32_16x16x32_bf16 v[84:87], v[152:155], v[176:179], v[84:87]
	v_mfma_f32_16x16x32_bf16 v[76:79], v[138:141], v[184:187], v[76:79]
	v_mfma_f32_16x16x32_bf16 v[68:71], v[152:155], v[184:187], v[68:71]
	v_mfma_f32_16x16x32_bf16 v[124:127], v[148:151], v[164:167], v[124:127]
	v_mfma_f32_16x16x32_bf16 v[116:119], v[156:159], v[164:167], v[116:119]
	v_mfma_f32_16x16x32_bf16 v[108:111], v[148:151], v[172:175], v[108:111]
	v_mfma_f32_16x16x32_bf16 v[100:103], v[156:159], v[172:175], v[100:103]
	v_mfma_f32_16x16x32_bf16 v[92:95], v[148:151], v[180:183], v[92:95]
	v_mfma_f32_16x16x32_bf16 v[84:87], v[156:159], v[180:183], v[84:87]
	v_mfma_f32_16x16x32_bf16 v[76:79], v[148:151], v[188:191], v[76:79]
	v_mfma_f32_16x16x32_bf16 v[68:71], v[156:159], v[188:191], v[68:71]
	s_setprio 0
	s_barrier
	s_add_i32 s44, 0, 0x14000
	v_add_u32_e32 v142, s44, v145
	s_add_i32 s41, s41, s28
	ds_read_b128 v[198:201], v142
	ds_read_b128 v[206:209], v142 offset:1024
	ds_read_b128 v[210:213], v142 offset:2048
	ds_read_b128 v[214:217], v142 offset:3072
	s_mov_b32 m0, s41
	s_nop 0
	global_load_lds_dwordx4 v192, s[20:21]
	s_add_i32 m0, s41, 0x2000
	s_nop 0
	global_load_lds_dwordx4 v128, s[20:21]
	s_barrier
	s_waitcnt lgkmcnt(0)
	s_setprio 1
	s_waitcnt lgkmcnt(0)
	v_mfma_f32_16x16x32_bf16 v[120:123], v[198:201], v[160:163], v[120:123]
	v_mfma_f32_16x16x32_bf16 v[112:115], v[210:213], v[160:163], v[112:115]
	v_mfma_f32_16x16x32_bf16 v[104:107], v[198:201], v[168:171], v[104:107]
	v_mfma_f32_16x16x32_bf16 v[96:99], v[210:213], v[168:171], v[96:99]
	v_mfma_f32_16x16x32_bf16 v[88:91], v[198:201], v[176:179], v[88:91]
	v_mfma_f32_16x16x32_bf16 v[80:83], v[210:213], v[176:179], v[80:83]
	v_mfma_f32_16x16x32_bf16 v[72:75], v[198:201], v[184:187], v[72:75]
	v_mfma_f32_16x16x32_bf16 v[64:67], v[210:213], v[184:187], v[64:67]
	v_mfma_f32_16x16x32_bf16 v[120:123], v[206:209], v[164:167], v[120:123]
	v_mfma_f32_16x16x32_bf16 v[112:115], v[214:217], v[164:167], v[112:115]
	v_mfma_f32_16x16x32_bf16 v[104:107], v[206:209], v[172:175], v[104:107]
	v_mfma_f32_16x16x32_bf16 v[96:99], v[214:217], v[172:175], v[96:99]
	v_mfma_f32_16x16x32_bf16 v[88:91], v[206:209], v[180:183], v[88:91]
	v_mfma_f32_16x16x32_bf16 v[80:83], v[214:217], v[180:183], v[80:83]
	v_mfma_f32_16x16x32_bf16 v[72:75], v[206:209], v[188:191], v[72:75]
	v_mfma_f32_16x16x32_bf16 v[64:67], v[214:217], v[188:191], v[64:67]
	s_setprio 0
	s_mov_b32 m0, s17
	s_add_u32 vcc_lo, s22, 0x80
	s_addc_u32 vcc_hi, s23, 0
	s_barrier
	ds_read_b128 v[160:163], v146 offset:16384
	ds_read_b128 v[164:167], v146 offset:17408
	ds_read_b128 v[168:171], v146 offset:18432
	ds_read_b128 v[172:175], v146 offset:19456
	ds_read_b128 v[176:179], v146 offset:20480
	ds_read_b128 v[180:183], v146 offset:21504
	ds_read_b128 v[184:187], v146 offset:22528
	ds_read_b128 v[188:191], v146 offset:23552
	global_load_lds_dwordx4 v132, s[22:23]
	s_mov_b32 m0, s29
	s_nop 0
	global_load_lds_dwordx4 v130, s[22:23]
	s_barrier
	s_waitcnt lgkmcnt(0)
	s_setprio 1
	s_waitcnt lgkmcnt(0)
	v_mfma_f32_16x16x32_bf16 v[60:63], v[138:141], v[160:163], v[60:63]
	v_mfma_f32_16x16x32_bf16 v[52:55], v[152:155], v[160:163], v[52:55]
	v_mfma_f32_16x16x32_bf16 v[44:47], v[138:141], v[168:171], v[44:47]
	v_mfma_f32_16x16x32_bf16 v[36:39], v[152:155], v[168:171], v[36:39]
	v_mfma_f32_16x16x32_bf16 v[28:31], v[138:141], v[176:179], v[28:31]
	v_mfma_f32_16x16x32_bf16 v[20:23], v[152:155], v[176:179], v[20:23]
	v_mfma_f32_16x16x32_bf16 v[12:15], v[138:141], v[184:187], v[12:15]
	v_mfma_f32_16x16x32_bf16 v[4:7], v[152:155], v[184:187], v[4:7]
	v_mfma_f32_16x16x32_bf16 v[60:63], v[148:151], v[164:167], v[60:63]
	v_mfma_f32_16x16x32_bf16 v[52:55], v[156:159], v[164:167], v[52:55]
	v_mfma_f32_16x16x32_bf16 v[44:47], v[148:151], v[172:175], v[44:47]
	v_mfma_f32_16x16x32_bf16 v[36:39], v[156:159], v[172:175], v[36:39]
	v_mfma_f32_16x16x32_bf16 v[28:31], v[148:151], v[180:183], v[28:31]
	v_mfma_f32_16x16x32_bf16 v[20:23], v[156:159], v[180:183], v[20:23]
	v_mfma_f32_16x16x32_bf16 v[12:15], v[148:151], v[188:191], v[12:15]
	v_mfma_f32_16x16x32_bf16 v[4:7], v[156:159], v[188:191], v[4:7]
	s_setprio 0
	s_barrier
	s_add_u32 s42, s20, 0x40000
	s_addc_u32 s43, s21, 0
	s_add_i32 s41, s44, s28
	s_mov_b32 m0, s41
	s_nop 0
	global_load_lds_dwordx4 v192, s[42:43]
	s_add_i32 m0, s41, 0x2000
	s_nop 0
	global_load_lds_dwordx4 v128, s[42:43]
	s_waitcnt vmcnt(6)
	s_barrier
	s_setprio 1
	v_mfma_f32_16x16x32_bf16 v[56:59], v[198:201], v[160:163], v[56:59]
	v_mfma_f32_16x16x32_bf16 v[48:51], v[210:213], v[160:163], v[48:51]
	v_mfma_f32_16x16x32_bf16 v[40:43], v[198:201], v[168:171], v[40:43]
	v_mfma_f32_16x16x32_bf16 v[32:35], v[210:213], v[168:171], v[32:35]
	v_mfma_f32_16x16x32_bf16 v[24:27], v[198:201], v[176:179], v[24:27]
	v_mfma_f32_16x16x32_bf16 v[16:19], v[210:213], v[176:179], v[16:19]
	v_mfma_f32_16x16x32_bf16 v[8:11], v[198:201], v[184:187], v[8:11]
	v_mfma_f32_16x16x32_bf16 v[0:3], v[210:213], v[184:187], v[0:3]
	v_mfma_f32_16x16x32_bf16 v[56:59], v[206:209], v[164:167], v[56:59]
	v_mfma_f32_16x16x32_bf16 v[48:51], v[214:217], v[164:167], v[48:51]
	v_mfma_f32_16x16x32_bf16 v[40:43], v[206:209], v[172:175], v[40:43]
	v_mfma_f32_16x16x32_bf16 v[32:35], v[214:217], v[172:175], v[32:35]
	v_mfma_f32_16x16x32_bf16 v[24:27], v[206:209], v[180:183], v[24:27]
	v_mfma_f32_16x16x32_bf16 v[16:19], v[214:217], v[180:183], v[16:19]
	v_mfma_f32_16x16x32_bf16 v[8:11], v[206:209], v[188:191], v[8:11]
	v_mfma_f32_16x16x32_bf16 v[0:3], v[214:217], v[188:191], v[0:3]
	s_setprio 0
	s_add_i32 s41, 0, 0x18000
	v_add_u32_e32 v144, s41, v145
	s_barrier
	ds_read_b128 v[138:141], v144
	ds_read_b128 v[148:151], v144 offset:1024
	ds_read_b128 v[152:155], v144 offset:2048
	ds_read_b128 v[156:159], v144 offset:3072
	s_add_u32 s22, s22, 0x40000
	s_addc_u32 s23, s23, 0
	s_mov_b32 m0, s30
	ds_read_b128 v[160:163], v146 offset:32768
	ds_read_b128 v[164:167], v146 offset:33792
	ds_read_b128 v[168:171], v146 offset:34816
	ds_read_b128 v[172:175], v146 offset:35840
	ds_read_b128 v[176:179], v146 offset:36864
	ds_read_b128 v[180:183], v146 offset:37888
	ds_read_b128 v[184:187], v146 offset:38912
	ds_read_b128 v[188:191], v146 offset:39936
	global_load_lds_dwordx4 v132, s[22:23]
	s_mov_b32 m0, s31
	s_nop 0
	global_load_lds_dwordx4 v130, s[22:23]
	s_waitcnt lgkmcnt(8)
	s_barrier
	s_waitcnt lgkmcnt(0)
	s_setprio 1
	s_waitcnt lgkmcnt(0)
	v_mfma_f32_16x16x32_bf16 v[124:127], v[138:141], v[160:163], v[124:127]
	v_mfma_f32_16x16x32_bf16 v[116:119], v[152:155], v[160:163], v[116:119]
	v_mfma_f32_16x16x32_bf16 v[108:111], v[138:141], v[168:171], v[108:111]
	v_mfma_f32_16x16x32_bf16 v[100:103], v[152:155], v[168:171], v[100:103]
	v_mfma_f32_16x16x32_bf16 v[92:95], v[138:141], v[176:179], v[92:95]
	v_mfma_f32_16x16x32_bf16 v[84:87], v[152:155], v[176:179], v[84:87]
	v_mfma_f32_16x16x32_bf16 v[76:79], v[138:141], v[184:187], v[76:79]
	v_mfma_f32_16x16x32_bf16 v[68:71], v[152:155], v[184:187], v[68:71]
	v_mfma_f32_16x16x32_bf16 v[124:127], v[148:151], v[164:167], v[124:127]
	v_mfma_f32_16x16x32_bf16 v[116:119], v[156:159], v[164:167], v[116:119]
	v_mfma_f32_16x16x32_bf16 v[108:111], v[148:151], v[172:175], v[108:111]
	v_mfma_f32_16x16x32_bf16 v[100:103], v[156:159], v[172:175], v[100:103]
	v_mfma_f32_16x16x32_bf16 v[92:95], v[148:151], v[180:183], v[92:95]
	v_mfma_f32_16x16x32_bf16 v[84:87], v[156:159], v[180:183], v[84:87]
	v_mfma_f32_16x16x32_bf16 v[76:79], v[148:151], v[188:191], v[76:79]
	v_mfma_f32_16x16x32_bf16 v[68:71], v[156:159], v[188:191], v[68:71]
	s_setprio 0
	s_barrier
	s_add_i32 s22, 0, 0x1c000
	s_add_i32 s23, s41, s28
	v_add_u32_e32 v144, s22, v145
	s_add_u32 s100, s20, 0x80
	s_addc_u32 s101, s21, 0
	s_mov_b32 m0, s23
	ds_read_b128 v[198:201], v144
	ds_read_b128 v[206:209], v144 offset:1024
	ds_read_b128 v[210:213], v144 offset:2048
	ds_read_b128 v[214:217], v144 offset:3072
	global_load_lds_dwordx4 v192, s[100:101]
	s_add_i32 m0, s23, 0x2000
	s_nop 0
	global_load_lds_dwordx4 v128, s[100:101]
	s_barrier
	s_waitcnt lgkmcnt(0)
	s_setprio 1
	s_waitcnt lgkmcnt(0)
	v_mfma_f32_16x16x32_bf16 v[120:123], v[198:201], v[160:163], v[120:123]
	v_mfma_f32_16x16x32_bf16 v[112:115], v[210:213], v[160:163], v[112:115]
	v_mfma_f32_16x16x32_bf16 v[104:107], v[198:201], v[168:171], v[104:107]
	v_mfma_f32_16x16x32_bf16 v[96:99], v[210:213], v[168:171], v[96:99]
	v_mfma_f32_16x16x32_bf16 v[88:91], v[198:201], v[176:179], v[88:91]
	v_mfma_f32_16x16x32_bf16 v[80:83], v[210:213], v[176:179], v[80:83]
	v_mfma_f32_16x16x32_bf16 v[72:75], v[198:201], v[184:187], v[72:75]
	v_mfma_f32_16x16x32_bf16 v[64:67], v[210:213], v[184:187], v[64:67]
	v_mfma_f32_16x16x32_bf16 v[120:123], v[206:209], v[164:167], v[120:123]
	v_mfma_f32_16x16x32_bf16 v[112:115], v[214:217], v[164:167], v[112:115]
	v_mfma_f32_16x16x32_bf16 v[104:107], v[206:209], v[172:175], v[104:107]
	v_mfma_f32_16x16x32_bf16 v[96:99], v[214:217], v[172:175], v[96:99]
	v_mfma_f32_16x16x32_bf16 v[88:91], v[206:209], v[180:183], v[88:91]
	v_mfma_f32_16x16x32_bf16 v[80:83], v[214:217], v[180:183], v[80:83]
	v_mfma_f32_16x16x32_bf16 v[72:75], v[206:209], v[188:191], v[72:75]
	v_mfma_f32_16x16x32_bf16 v[64:67], v[214:217], v[188:191], v[64:67]
	s_setprio 0
	s_mov_b32 m0, s34
	s_barrier
	ds_read_b128 v[160:163], v146 offset:49152
	ds_read_b128 v[164:167], v146 offset:50176
	ds_read_b128 v[168:171], v146 offset:51200
	ds_read_b128 v[172:175], v146 offset:52224
	ds_read_b128 v[176:179], v146 offset:53248
	ds_read_b128 v[180:183], v146 offset:54272
	ds_read_b128 v[184:187], v146 offset:55296
	ds_read_b128 v[188:191], v146 offset:56320
	global_load_lds_dwordx4 v132, vcc
	s_mov_b32 m0, s35
	s_nop 0
	global_load_lds_dwordx4 v130, vcc
	s_barrier
	s_waitcnt lgkmcnt(0)
	s_setprio 1
	s_waitcnt lgkmcnt(0)
	v_mfma_f32_16x16x32_bf16 v[60:63], v[138:141], v[160:163], v[60:63]
	v_mfma_f32_16x16x32_bf16 v[52:55], v[152:155], v[160:163], v[52:55]
	v_mfma_f32_16x16x32_bf16 v[44:47], v[138:141], v[168:171], v[44:47]
	v_mfma_f32_16x16x32_bf16 v[36:39], v[152:155], v[168:171], v[36:39]
	v_mfma_f32_16x16x32_bf16 v[28:31], v[138:141], v[176:179], v[28:31]
	v_mfma_f32_16x16x32_bf16 v[20:23], v[152:155], v[176:179], v[20:23]
	v_mfma_f32_16x16x32_bf16 v[12:15], v[138:141], v[184:187], v[12:15]
	v_mfma_f32_16x16x32_bf16 v[4:7], v[152:155], v[184:187], v[4:7]
	v_mfma_f32_16x16x32_bf16 v[60:63], v[148:151], v[164:167], v[60:63]
	v_mfma_f32_16x16x32_bf16 v[52:55], v[156:159], v[164:167], v[52:55]
	v_mfma_f32_16x16x32_bf16 v[44:47], v[148:151], v[172:175], v[44:47]
	v_mfma_f32_16x16x32_bf16 v[36:39], v[156:159], v[172:175], v[36:39]
	v_mfma_f32_16x16x32_bf16 v[28:31], v[148:151], v[180:183], v[28:31]
	v_mfma_f32_16x16x32_bf16 v[20:23], v[156:159], v[180:183], v[20:23]
	v_mfma_f32_16x16x32_bf16 v[12:15], v[148:151], v[188:191], v[12:15]
	v_mfma_f32_16x16x32_bf16 v[4:7], v[156:159], v[188:191], v[4:7]
	s_setprio 0
	s_barrier
	s_add_u32 s20, s20, 0x40080
	s_addc_u32 s21, s21, 0
	s_add_i32 s22, s22, s28
	s_mov_b32 m0, s22
	s_nop 0
	global_load_lds_dwordx4 v192, s[20:21]
	s_add_i32 m0, s22, 0x2000
	s_nop 0
	global_load_lds_dwordx4 v128, s[20:21]
	s_waitcnt vmcnt(6)
	s_barrier
	s_setprio 1
	v_mfma_f32_16x16x32_bf16 v[56:59], v[198:201], v[160:163], v[56:59]
	v_mfma_f32_16x16x32_bf16 v[48:51], v[210:213], v[160:163], v[48:51]
	v_mfma_f32_16x16x32_bf16 v[40:43], v[198:201], v[168:171], v[40:43]
	v_mfma_f32_16x16x32_bf16 v[32:35], v[210:213], v[168:171], v[32:35]
	v_mfma_f32_16x16x32_bf16 v[24:27], v[198:201], v[176:179], v[24:27]
	v_mfma_f32_16x16x32_bf16 v[16:19], v[210:213], v[176:179], v[16:19]
	v_mfma_f32_16x16x32_bf16 v[8:11], v[198:201], v[184:187], v[8:11]
	v_mfma_f32_16x16x32_bf16 v[0:3], v[210:213], v[184:187], v[0:3]
	v_mfma_f32_16x16x32_bf16 v[56:59], v[206:209], v[164:167], v[56:59]
	v_mfma_f32_16x16x32_bf16 v[48:51], v[214:217], v[164:167], v[48:51]
	v_mfma_f32_16x16x32_bf16 v[40:43], v[206:209], v[172:175], v[40:43]
	v_mfma_f32_16x16x32_bf16 v[32:35], v[214:217], v[172:175], v[32:35]
	v_mfma_f32_16x16x32_bf16 v[24:27], v[206:209], v[180:183], v[24:27]
	v_mfma_f32_16x16x32_bf16 v[16:19], v[214:217], v[180:183], v[16:19]
	v_mfma_f32_16x16x32_bf16 v[8:11], v[206:209], v[188:191], v[8:11]
	v_mfma_f32_16x16x32_bf16 v[0:3], v[214:217], v[188:191], v[0:3]
	s_setprio 0
	s_add_i32 s40, s40, 2
	s_add_u32 s38, s38, 0x100
	s_addc_u32 s39, s39, 0
	s_add_u32 s18, s18, 0x100
	s_addc_u32 s19, s19, 0
	s_cmp_gt_u32 s40, 13
	s_barrier
	s_cbranch_scc0 .LBB0_402
	v_mov_b32_e32 v139, v252
	s_lshl_b32 s9, s16, 8
	v_readfirstlane_b32 s1, v139
	s_ashr_i32 s11, s1, 2
	s_andn2_b32 s11, s11, 63
	s_lshr_b32 s1, s1, 1
	s_add_i32 s11, s11, s9
	s_lshl_b32 s0, s0, 7
	s_and_b32 s1, s1, 0x60
	v_and_or_b32 v138, v139, 15, s11
	s_or_b32 s0, s1, s0
	v_lshrrev_b32_e32 v139, 1, v139
	v_and_or_b32 v142, v139, 24, s0
	v_ashrrev_i32_e32 v139, 31, v138
	v_lshl_add_u64 v[140:141], v[138:139], 2, s[6:7]
	v_pk_mul_f32 v[120:121], v[124:125], v[120:121]
	v_pk_mul_f32 v[122:123], v[126:127], v[122:123]
	v_pk_mul_f32 v[112:113], v[116:117], v[112:113]
	v_pk_mul_f32 v[114:115], v[118:119], v[114:115]
	v_ashrrev_i32_e32 v143, 31, v142
	s_movk_i32 s9, 0x1600
	v_pk_mul_f32 v[104:105], v[108:109], v[104:105]
	v_pk_mul_f32 v[106:107], v[110:111], v[106:107]
	v_pk_mul_f32 v[96:97], v[100:101], v[96:97]
	v_or_b32_e32 v150, 16, v138
	v_pk_mul_f32 v[98:99], v[102:103], v[98:99]
	v_pk_mul_f32 v[88:89], v[92:93], v[88:89]
	v_pk_mul_f32 v[90:91], v[94:95], v[90:91]
	v_pk_mul_f32 v[80:81], v[84:85], v[80:81]
	v_or_b32_e32 v148, 32, v138
	v_pk_mul_f32 v[82:83], v[86:87], v[82:83]
	v_pk_mul_f32 v[72:73], v[76:77], v[72:73]
	v_pk_mul_f32 v[74:75], v[78:79], v[74:75]
	v_pk_mul_f32 v[64:65], v[68:69], v[64:65]
	v_or_b32_e32 v139, 48, v138
	v_pk_mul_f32 v[66:67], v[70:71], v[66:67]
	v_pk_mul_f32 v[56:57], v[60:61], v[56:57]
	v_pk_mul_f32 v[58:59], v[62:63], v[58:59]
	v_pk_mul_f32 v[48:49], v[52:53], v[48:49]
	v_pk_mul_f32 v[50:51], v[54:55], v[50:51]
	v_pk_mul_f32 v[40:41], v[44:45], v[40:41]
	v_pk_mul_f32 v[42:43], v[46:47], v[42:43]
	v_pk_mul_f32 v[32:33], v[36:37], v[32:33]
	v_pk_mul_f32 v[34:35], v[38:39], v[34:35]
	v_pk_mul_f32 v[24:25], v[28:29], v[24:25]
	v_pk_mul_f32 v[26:27], v[30:31], v[26:27]
	v_pk_mul_f32 v[16:17], v[20:21], v[16:17]
	v_pk_mul_f32 v[18:19], v[22:23], v[18:19]
	v_pk_mul_f32 v[8:9], v[12:13], v[8:9]
	v_pk_mul_f32 v[10:11], v[14:15], v[10:11]
	v_pk_mul_f32 v[0:1], v[4:5], v[0:1]
	v_pk_mul_f32 v[2:3], v[6:7], v[2:3]
	s_mov_b32 s16, s8
	s_mov_b64 s[18:19], s[14:15]
	s_mov_b64 s[20:21], s[12:13]
	v_fmamk_f32 v144, v231, 0x3a800000, v194
	v_cmp_gt_f32_e32 vcc, s2, v144
	v_mul_f32_e32 v152, 0x4b800000, v144
	s_nop 0
	v_cndmask_b32_e32 v144, v144, v152, vcc
	v_rsq_f32_e32 v144, v144
	s_nop 0
	v_mul_f32_e32 v152, 0x45800000, v144
	v_cndmask_b32_e32 v144, v144, v152, vcc
	v_mul_f32_e32 v152, 0xbfb8aa3b, v144
	v_pk_mul_f32 v[156:157], v[124:125], v[152:153] op_sel_hi:[1,0]
	v_pk_mul_f32 v[154:155], v[126:127], v[152:153] op_sel_hi:[1,0]
	v_exp_f32_e32 v153, v156
	v_mul_f32_e32 v144, v144, v144
	v_add_f32_e32 v153, 1.0, v153
	v_rcp_f32_e32 v156, v153
	v_exp_f32_e32 v153, v157
	s_nop 0
	v_add_f32_e32 v153, 1.0, v153
	v_rcp_f32_e32 v157, v153
	v_exp_f32_e32 v153, v154
	v_pk_mul_f32 v[124:125], v[144:145], v[156:157] op_sel_hi:[0,1]
	v_add_f32_e32 v153, 1.0, v153
	v_rcp_f32_e32 v154, v153
	v_exp_f32_e32 v153, v155
	v_pk_mul_f32 v[120:121], v[120:121], v[124:125]
	v_add_f32_e32 v153, 1.0, v153
	v_rcp_f32_e32 v155, v153
	v_cvt_pk_bf16_f32 v124, v121, s0
	v_cvt_pk_bf16_f32 v120, v120, s0
	v_readlane_b32 s0, v254, 29
	v_pk_mul_f32 v[126:127], v[144:145], v[154:155] op_sel_hi:[0,1]
	v_pk_mul_f32 v[122:123], v[122:123], v[126:127]
	v_readlane_b32 s1, v254, 30
	v_cvt_pk_bf16_f32 v121, v122, v123
	v_lshlrev_b32_e32 v122, 16, v124
	v_pk_mul_f32 v[124:125], v[116:117], v[152:153] op_sel_hi:[1,0]
	v_or_b32_sdwa v120, v122, v120 dst_sel:DWORD dst_unused:UNUSED_PAD src0_sel:DWORD src1_sel:WORD_0
	v_pk_mul_f32 v[122:123], v[118:119], v[152:153] op_sel_hi:[1,0]
	v_exp_f32_e32 v124, v124
	v_exp_f32_e32 v125, v125
	v_exp_f32_e32 v122, v122
	v_exp_f32_e32 v123, v123
	v_add_f32_e32 v124, 1.0, v124
	v_add_f32_e32 v125, 1.0, v125
	v_rcp_f32_e32 v124, v124
	v_rcp_f32_e32 v125, v125
	v_add_f32_e32 v122, 1.0, v122
	v_add_f32_e32 v123, 1.0, v123
	v_rcp_f32_e32 v122, v122
	v_rcp_f32_e32 v123, v123
	v_pk_mul_f32 v[116:117], v[144:145], v[124:125] op_sel_hi:[0,1]
	v_pk_mul_f32 v[112:113], v[112:113], v[116:117]
	v_pk_mul_f32 v[118:119], v[144:145], v[122:123] op_sel_hi:[0,1]
	v_pk_mul_f32 v[114:115], v[114:115], v[118:119]
	v_cvt_pk_bf16_f32 v122, v112, v113
	v_mov_b64_e32 v[112:113], s[0:1]
	v_cvt_pk_bf16_f32 v123, v114, v115
	v_mad_i64_i32 v[116:117], s[0:1], v138, s9, v[112:113]
	v_lshlrev_b64 v[114:115], 1, v[142:143]
	v_lshl_add_u64 v[116:117], v[116:117], 0, v[114:115]
	global_store_dwordx4 v[116:117], v[120:123], off
	v_fmamk_f32 v116, v232, 0x3a800000, v194
	v_cmp_gt_f32_e32 vcc, s2, v116
	v_mul_f32_e32 v117, 0x4b800000, v116
	s_nop 0
	v_cndmask_b32_e32 v116, v116, v117, vcc
	v_rsq_f32_e32 v116, v116
	s_nop 0
	v_mul_f32_e32 v117, 0x45800000, v116
	v_cndmask_b32_e32 v116, v116, v117, vcc
	v_mul_f32_e32 v118, 0xbfb8aa3b, v116
	v_pk_mul_f32 v[120:121], v[108:109], v[118:119] op_sel_hi:[1,0]
	v_pk_mul_f32 v[122:123], v[110:111], v[118:119] op_sel_hi:[1,0]
	v_exp_f32_e32 v117, v120
	v_mul_f32_e32 v116, v116, v116
	v_add_f32_e32 v117, 1.0, v117
	v_rcp_f32_e32 v120, v117
	v_exp_f32_e32 v117, v121
	s_nop 0
	v_add_f32_e32 v117, 1.0, v117
	v_rcp_f32_e32 v121, v117
	v_exp_f32_e32 v117, v122
	s_nop 0
	v_add_f32_e32 v117, 1.0, v117
	v_rcp_f32_e32 v122, v117
	v_exp_f32_e32 v117, v123
	s_nop 0
	v_add_f32_e32 v117, 1.0, v117
	v_rcp_f32_e32 v123, v117
	v_pk_mul_f32 v[108:109], v[116:117], v[120:121] op_sel_hi:[0,1]
	v_pk_mul_f32 v[104:105], v[104:105], v[108:109]
	v_pk_mul_f32 v[110:111], v[116:117], v[122:123] op_sel_hi:[0,1]
	v_pk_mul_f32 v[106:107], v[106:107], v[110:111]
	v_cvt_pk_bf16_f32 v108, v105, s0
	v_cvt_pk_bf16_f32 v104, v104, s0
	v_cvt_pk_bf16_f32 v105, v106, v107
	v_lshlrev_b32_e32 v106, 16, v108
	v_pk_mul_f32 v[108:109], v[100:101], v[118:119] op_sel_hi:[1,0]
	v_or_b32_sdwa v104, v106, v104 dst_sel:DWORD dst_unused:UNUSED_PAD src0_sel:DWORD src1_sel:WORD_0
	v_pk_mul_f32 v[106:107], v[102:103], v[118:119] op_sel_hi:[1,0]
	v_exp_f32_e32 v108, v108
	v_exp_f32_e32 v109, v109
	v_exp_f32_e32 v106, v106
	v_exp_f32_e32 v107, v107
	v_add_f32_e32 v108, 1.0, v108
	v_add_f32_e32 v109, 1.0, v109
	v_rcp_f32_e32 v108, v108
	v_rcp_f32_e32 v109, v109
	v_add_f32_e32 v106, 1.0, v106
	v_add_f32_e32 v107, 1.0, v107
	v_rcp_f32_e32 v106, v106
	v_rcp_f32_e32 v107, v107
	v_pk_mul_f32 v[100:101], v[116:117], v[108:109] op_sel_hi:[0,1]
	v_pk_mul_f32 v[96:97], v[96:97], v[100:101]
	v_pk_mul_f32 v[102:103], v[116:117], v[106:107] op_sel_hi:[0,1]
	v_pk_mul_f32 v[98:99], v[98:99], v[102:103]
	v_cvt_pk_bf16_f32 v106, v96, v97
	v_mad_i64_i32 v[96:97], s[0:1], v150, s9, v[112:113]
	v_cvt_pk_bf16_f32 v107, v98, v99
	v_lshl_add_u64 v[96:97], v[96:97], 0, v[114:115]
	global_store_dwordx4 v[96:97], v[104:107], off
	v_fmamk_f32 v96, v233, 0x3a800000, v194
	v_cmp_gt_f32_e32 vcc, s2, v96
	v_mul_f32_e32 v97, 0x4b800000, v96
	s_nop 0
	v_cndmask_b32_e32 v96, v96, v97, vcc
	v_rsq_f32_e32 v96, v96
	s_nop 0
	v_mul_f32_e32 v97, 0x45800000, v96
	v_cndmask_b32_e32 v97, v96, v97, vcc
	v_mul_f32_e32 v96, 0xbfb8aa3b, v97
	v_pk_mul_f32 v[102:103], v[92:93], v[96:97] op_sel_hi:[1,0]
	v_mul_f32_e32 v98, v97, v97
	v_pk_mul_f32 v[100:101], v[94:95], v[96:97] op_sel_hi:[1,0]
	v_exp_f32_e32 v97, v102
	s_nop 0
	v_add_f32_e32 v97, 1.0, v97
	v_rcp_f32_e32 v102, v97
	v_exp_f32_e32 v97, v103
	s_nop 0
	v_add_f32_e32 v97, 1.0, v97
	v_rcp_f32_e32 v103, v97
	v_exp_f32_e32 v97, v100
	v_pk_mul_f32 v[92:93], v[98:99], v[102:103] op_sel_hi:[0,1]
	v_add_f32_e32 v97, 1.0, v97
	v_rcp_f32_e32 v100, v97
	v_exp_f32_e32 v97, v101
	v_pk_mul_f32 v[88:89], v[88:89], v[92:93]
	v_add_f32_e32 v97, 1.0, v97
	v_rcp_f32_e32 v101, v97
	v_cvt_pk_bf16_f32 v92, v89, s0
	v_cvt_pk_bf16_f32 v88, v88, s0
	v_pk_mul_f32 v[94:95], v[98:99], v[100:101] op_sel_hi:[0,1]
	v_pk_mul_f32 v[90:91], v[90:91], v[94:95]
	s_nop 0
	v_cvt_pk_bf16_f32 v89, v90, v91
	v_lshlrev_b32_e32 v90, 16, v92
	v_pk_mul_f32 v[92:93], v[84:85], v[96:97] op_sel_hi:[1,0]
	v_or_b32_sdwa v88, v90, v88 dst_sel:DWORD dst_unused:UNUSED_PAD src0_sel:DWORD src1_sel:WORD_0
	v_pk_mul_f32 v[90:91], v[86:87], v[96:97] op_sel_hi:[1,0]
	v_exp_f32_e32 v92, v92
	v_exp_f32_e32 v93, v93
	v_exp_f32_e32 v90, v90
	v_exp_f32_e32 v91, v91
	v_add_f32_e32 v92, 1.0, v92
	v_add_f32_e32 v93, 1.0, v93
	v_rcp_f32_e32 v92, v92
	v_rcp_f32_e32 v93, v93
	v_add_f32_e32 v90, 1.0, v90
	v_add_f32_e32 v91, 1.0, v91
	v_rcp_f32_e32 v90, v90
	v_rcp_f32_e32 v91, v91
	v_pk_mul_f32 v[84:85], v[98:99], v[92:93] op_sel_hi:[0,1]
	v_pk_mul_f32 v[80:81], v[80:81], v[84:85]
	v_pk_mul_f32 v[86:87], v[98:99], v[90:91] op_sel_hi:[0,1]
	v_pk_mul_f32 v[82:83], v[82:83], v[86:87]
	v_cvt_pk_bf16_f32 v90, v80, v81
	v_mad_i64_i32 v[80:81], s[0:1], v148, s9, v[112:113]
	v_cvt_pk_bf16_f32 v91, v82, v83
	v_lshl_add_u64 v[80:81], v[80:81], 0, v[114:115]
	global_store_dwordx4 v[80:81], v[88:91], off
	v_fmamk_f32 v80, v234, 0x3a800000, v194
	v_cmp_gt_f32_e32 vcc, s2, v80
	v_mul_f32_e32 v81, 0x4b800000, v80
	s_nop 0
	v_cndmask_b32_e32 v80, v80, v81, vcc
	v_rsq_f32_e32 v80, v80
	s_nop 0
	v_mul_f32_e32 v81, 0x45800000, v80
	v_cndmask_b32_e32 v81, v80, v81, vcc
	v_mul_f32_e32 v80, 0xbfb8aa3b, v81
	v_pk_mul_f32 v[86:87], v[76:77], v[80:81] op_sel_hi:[1,0]
	v_mul_f32_e32 v82, v81, v81
	v_pk_mul_f32 v[84:85], v[78:79], v[80:81] op_sel_hi:[1,0]
	v_exp_f32_e32 v81, v86
	s_nop 0
	v_add_f32_e32 v81, 1.0, v81
	v_rcp_f32_e32 v86, v81
	v_exp_f32_e32 v81, v87
	s_nop 0
	v_add_f32_e32 v81, 1.0, v81
	v_rcp_f32_e32 v87, v81
	v_exp_f32_e32 v81, v84
	v_pk_mul_f32 v[76:77], v[82:83], v[86:87] op_sel_hi:[0,1]
	v_add_f32_e32 v81, 1.0, v81
	v_rcp_f32_e32 v84, v81
	v_exp_f32_e32 v81, v85
	v_pk_mul_f32 v[72:73], v[72:73], v[76:77]
	v_add_f32_e32 v81, 1.0, v81
	v_rcp_f32_e32 v85, v81
	v_cvt_pk_bf16_f32 v76, v73, s0
	v_cvt_pk_bf16_f32 v72, v72, s0
	v_pk_mul_f32 v[78:79], v[82:83], v[84:85] op_sel_hi:[0,1]
	v_pk_mul_f32 v[74:75], v[74:75], v[78:79]
	s_nop 0
	v_cvt_pk_bf16_f32 v73, v74, v75
	v_lshlrev_b32_e32 v74, 16, v76
	v_pk_mul_f32 v[76:77], v[68:69], v[80:81] op_sel_hi:[1,0]
	v_or_b32_sdwa v72, v74, v72 dst_sel:DWORD dst_unused:UNUSED_PAD src0_sel:DWORD src1_sel:WORD_0
	v_pk_mul_f32 v[74:75], v[70:71], v[80:81] op_sel_hi:[1,0]
	v_exp_f32_e32 v76, v76
	v_exp_f32_e32 v77, v77
	v_exp_f32_e32 v74, v74
	v_exp_f32_e32 v75, v75
	v_add_f32_e32 v76, 1.0, v76
	v_add_f32_e32 v77, 1.0, v77
	v_rcp_f32_e32 v76, v76
	v_rcp_f32_e32 v77, v77
	v_add_f32_e32 v74, 1.0, v74
	v_add_f32_e32 v75, 1.0, v75
	v_rcp_f32_e32 v74, v74
	v_rcp_f32_e32 v75, v75
	v_pk_mul_f32 v[68:69], v[82:83], v[76:77] op_sel_hi:[0,1]
	v_pk_mul_f32 v[64:65], v[64:65], v[68:69]
	v_add_u32_e32 v69, 0x90, v138
	v_pk_mul_f32 v[70:71], v[82:83], v[74:75] op_sel_hi:[0,1]
	v_pk_mul_f32 v[66:67], v[66:67], v[70:71]
	v_cvt_pk_bf16_f32 v74, v64, v65
	v_mad_i64_i32 v[64:65], s[0:1], v139, s9, v[112:113]
	v_cvt_pk_bf16_f32 v75, v66, v67
	v_lshl_add_u64 v[64:65], v[64:65], 0, v[114:115]
	global_store_dwordx4 v[64:65], v[72:75], off
	v_add_u32_e32 v67, 0x80, v138
	v_add_u32_e32 v66, 0xa0, v138
	v_add_u32_e32 v64, 0xb0, v138
	v_fmamk_f32 v68, v235, 0x3a800000, v194
	v_cmp_gt_f32_e32 vcc, s2, v68
	v_mul_f32_e32 v70, 0x4b800000, v68
	s_nop 0
	v_cndmask_b32_e32 v68, v68, v70, vcc
	v_rsq_f32_e32 v68, v68
	s_nop 0
	v_mul_f32_e32 v70, 0x45800000, v68
	v_cndmask_b32_e32 v70, v68, v70, vcc
	v_mul_f32_e32 v68, 0xbfb8aa3b, v70
	v_pk_mul_f32 v[74:75], v[60:61], v[68:69] op_sel_hi:[1,0]
	v_pk_mul_f32 v[72:73], v[62:63], v[68:69] op_sel_hi:[1,0]
	v_exp_f32_e32 v74, v74
	v_exp_f32_e32 v75, v75
	v_exp_f32_e32 v72, v72
	v_exp_f32_e32 v73, v73
	v_add_f32_e32 v74, 1.0, v74
	v_add_f32_e32 v75, 1.0, v75
	v_rcp_f32_e32 v74, v74
	v_rcp_f32_e32 v75, v75
	v_add_f32_e32 v72, 1.0, v72
	v_add_f32_e32 v73, 1.0, v73
	v_rcp_f32_e32 v72, v72
	v_rcp_f32_e32 v73, v73
	v_mul_f32_e32 v70, v70, v70
	v_pk_mul_f32 v[60:61], v[70:71], v[74:75] op_sel_hi:[0,1]
	v_pk_mul_f32 v[56:57], v[56:57], v[60:61]
	v_pk_mul_f32 v[62:63], v[70:71], v[72:73] op_sel_hi:[0,1]
	v_pk_mul_f32 v[58:59], v[58:59], v[62:63]
	v_cvt_pk_bf16_f32 v60, v57, s0
	v_cvt_pk_bf16_f32 v56, v56, s0
	v_cvt_pk_bf16_f32 v57, v58, v59
	v_lshlrev_b32_e32 v58, 16, v60
	v_pk_mul_f32 v[60:61], v[52:53], v[68:69] op_sel_hi:[1,0]
	v_or_b32_sdwa v56, v58, v56 dst_sel:DWORD dst_unused:UNUSED_PAD src0_sel:DWORD src1_sel:WORD_0
	v_pk_mul_f32 v[58:59], v[54:55], v[68:69] op_sel_hi:[1,0]
	v_exp_f32_e32 v60, v60
	v_exp_f32_e32 v61, v61
	v_exp_f32_e32 v58, v58
	v_exp_f32_e32 v59, v59
	v_add_f32_e32 v60, 1.0, v60
	v_add_f32_e32 v61, 1.0, v61
	v_rcp_f32_e32 v60, v60
	v_rcp_f32_e32 v61, v61
	v_add_f32_e32 v58, 1.0, v58
	v_add_f32_e32 v59, 1.0, v59
	v_rcp_f32_e32 v58, v58
	v_rcp_f32_e32 v59, v59
	v_pk_mul_f32 v[52:53], v[70:71], v[60:61] op_sel_hi:[0,1]
	v_pk_mul_f32 v[48:49], v[48:49], v[52:53]
	v_pk_mul_f32 v[54:55], v[70:71], v[58:59] op_sel_hi:[0,1]
	v_pk_mul_f32 v[50:51], v[50:51], v[54:55]
	v_cvt_pk_bf16_f32 v58, v48, v49
	v_mad_i64_i32 v[48:49], s[0:1], v67, s9, v[112:113]
	v_cvt_pk_bf16_f32 v59, v50, v51
	v_lshl_add_u64 v[48:49], v[48:49], 0, v[114:115]
	global_store_dwordx4 v[48:49], v[56:59], off
	v_fmamk_f32 v48, v236, 0x3a800000, v194
	v_cmp_gt_f32_e32 vcc, s2, v48
	v_mul_f32_e32 v49, 0x4b800000, v48
	s_nop 0
	v_cndmask_b32_e32 v48, v48, v49, vcc
	v_rsq_f32_e32 v48, v48
	s_nop 0
	v_mul_f32_e32 v49, 0x45800000, v48
	v_cndmask_b32_e32 v49, v48, v49, vcc
	v_mul_f32_e32 v48, 0xbfb8aa3b, v49
	v_pk_mul_f32 v[54:55], v[44:45], v[48:49] op_sel_hi:[1,0]
	v_mul_f32_e32 v50, v49, v49
	v_pk_mul_f32 v[52:53], v[46:47], v[48:49] op_sel_hi:[1,0]
	v_exp_f32_e32 v49, v54
	s_nop 0
	v_add_f32_e32 v49, 1.0, v49
	v_rcp_f32_e32 v54, v49
	v_exp_f32_e32 v49, v55
	s_nop 0
	v_add_f32_e32 v49, 1.0, v49
	v_rcp_f32_e32 v55, v49
	v_exp_f32_e32 v49, v52
	v_pk_mul_f32 v[44:45], v[50:51], v[54:55] op_sel_hi:[0,1]
	v_add_f32_e32 v49, 1.0, v49
	v_rcp_f32_e32 v52, v49
	v_exp_f32_e32 v49, v53
	v_pk_mul_f32 v[40:41], v[40:41], v[44:45]
	v_add_f32_e32 v49, 1.0, v49
	v_rcp_f32_e32 v53, v49
	v_cvt_pk_bf16_f32 v44, v41, s0
	v_cvt_pk_bf16_f32 v40, v40, s0
	v_pk_mul_f32 v[46:47], v[50:51], v[52:53] op_sel_hi:[0,1]
	v_pk_mul_f32 v[42:43], v[42:43], v[46:47]
	s_nop 0
	v_cvt_pk_bf16_f32 v41, v42, v43
	v_lshlrev_b32_e32 v42, 16, v44
	v_pk_mul_f32 v[44:45], v[36:37], v[48:49] op_sel_hi:[1,0]
	v_or_b32_sdwa v40, v42, v40 dst_sel:DWORD dst_unused:UNUSED_PAD src0_sel:DWORD src1_sel:WORD_0
	v_pk_mul_f32 v[42:43], v[38:39], v[48:49] op_sel_hi:[1,0]
	v_exp_f32_e32 v44, v44
	v_exp_f32_e32 v45, v45
	v_exp_f32_e32 v42, v42
	v_exp_f32_e32 v43, v43
	v_add_f32_e32 v44, 1.0, v44
	v_add_f32_e32 v45, 1.0, v45
	v_rcp_f32_e32 v44, v44
	v_rcp_f32_e32 v45, v45
	v_add_f32_e32 v42, 1.0, v42
	v_add_f32_e32 v43, 1.0, v43
	v_rcp_f32_e32 v42, v42
	v_rcp_f32_e32 v43, v43
	v_pk_mul_f32 v[36:37], v[50:51], v[44:45] op_sel_hi:[0,1]
	v_pk_mul_f32 v[32:33], v[32:33], v[36:37]
	v_pk_mul_f32 v[38:39], v[50:51], v[42:43] op_sel_hi:[0,1]
	v_pk_mul_f32 v[34:35], v[34:35], v[38:39]
	v_cvt_pk_bf16_f32 v42, v32, v33
	v_mad_i64_i32 v[32:33], s[0:1], v69, s9, v[112:113]
	v_cvt_pk_bf16_f32 v43, v34, v35
	v_lshl_add_u64 v[32:33], v[32:33], 0, v[114:115]
	global_store_dwordx4 v[32:33], v[40:43], off
	v_fmamk_f32 v32, v237, 0x3a800000, v194
	v_cmp_gt_f32_e32 vcc, s2, v32
	v_mul_f32_e32 v33, 0x4b800000, v32
	s_nop 0
	v_cndmask_b32_e32 v32, v32, v33, vcc
	v_rsq_f32_e32 v32, v32
	s_nop 0
	v_mul_f32_e32 v33, 0x45800000, v32
	v_cndmask_b32_e32 v33, v32, v33, vcc
	v_mul_f32_e32 v32, 0xbfb8aa3b, v33
	v_pk_mul_f32 v[38:39], v[28:29], v[32:33] op_sel_hi:[1,0]
	v_mul_f32_e32 v34, v33, v33
	v_pk_mul_f32 v[36:37], v[30:31], v[32:33] op_sel_hi:[1,0]
	v_exp_f32_e32 v33, v38
	s_nop 0
	v_add_f32_e32 v33, 1.0, v33
	v_rcp_f32_e32 v38, v33
	v_exp_f32_e32 v33, v39
	s_nop 0
	v_add_f32_e32 v33, 1.0, v33
	v_rcp_f32_e32 v39, v33
	v_exp_f32_e32 v33, v36
	v_pk_mul_f32 v[28:29], v[34:35], v[38:39] op_sel_hi:[0,1]
	v_add_f32_e32 v33, 1.0, v33
	v_rcp_f32_e32 v36, v33
	v_exp_f32_e32 v33, v37
	v_pk_mul_f32 v[24:25], v[24:25], v[28:29]
	v_add_f32_e32 v33, 1.0, v33
	v_rcp_f32_e32 v37, v33
	v_cvt_pk_bf16_f32 v28, v25, s0
	v_cvt_pk_bf16_f32 v24, v24, s0
	v_pk_mul_f32 v[30:31], v[34:35], v[36:37] op_sel_hi:[0,1]
	v_pk_mul_f32 v[26:27], v[26:27], v[30:31]
	s_nop 0
	v_cvt_pk_bf16_f32 v25, v26, v27
	v_lshlrev_b32_e32 v26, 16, v28
	v_pk_mul_f32 v[28:29], v[20:21], v[32:33] op_sel_hi:[1,0]
	v_or_b32_sdwa v24, v26, v24 dst_sel:DWORD dst_unused:UNUSED_PAD src0_sel:DWORD src1_sel:WORD_0
	v_pk_mul_f32 v[26:27], v[22:23], v[32:33] op_sel_hi:[1,0]
	v_exp_f32_e32 v28, v28
	v_exp_f32_e32 v29, v29
	v_exp_f32_e32 v26, v26
	v_exp_f32_e32 v27, v27
	v_add_f32_e32 v28, 1.0, v28
	v_add_f32_e32 v29, 1.0, v29
	v_rcp_f32_e32 v28, v28
	v_rcp_f32_e32 v29, v29
	v_add_f32_e32 v26, 1.0, v26
	v_add_f32_e32 v27, 1.0, v27
	v_rcp_f32_e32 v26, v26
	v_rcp_f32_e32 v27, v27
	v_pk_mul_f32 v[20:21], v[34:35], v[28:29] op_sel_hi:[0,1]
	v_pk_mul_f32 v[16:17], v[16:17], v[20:21]
	v_pk_mul_f32 v[22:23], v[34:35], v[26:27] op_sel_hi:[0,1]
	v_pk_mul_f32 v[18:19], v[18:19], v[22:23]
	v_cvt_pk_bf16_f32 v26, v16, v17
	v_mad_i64_i32 v[16:17], s[0:1], v66, s9, v[112:113]
	v_cvt_pk_bf16_f32 v27, v18, v19
	v_lshl_add_u64 v[16:17], v[16:17], 0, v[114:115]
	global_store_dwordx4 v[16:17], v[24:27], off
	v_fmamk_f32 v16, v238, 0x3a800000, v194
	v_cmp_gt_f32_e32 vcc, s2, v16
	v_mul_f32_e32 v17, 0x4b800000, v16
	s_nop 0
	v_cndmask_b32_e32 v16, v16, v17, vcc
	v_rsq_f32_e32 v16, v16
	s_nop 0
	v_mul_f32_e32 v17, 0x45800000, v16
	v_cndmask_b32_e32 v17, v16, v17, vcc
	v_mul_f32_e32 v16, 0xbfb8aa3b, v17
	v_pk_mul_f32 v[22:23], v[12:13], v[16:17] op_sel_hi:[1,0]
	v_mul_f32_e32 v18, v17, v17
	v_pk_mul_f32 v[20:21], v[14:15], v[16:17] op_sel_hi:[1,0]
	v_exp_f32_e32 v17, v22
	s_and_b64 vcc, exec, s[4:5]
	v_add_f32_e32 v17, 1.0, v17
	v_rcp_f32_e32 v22, v17
	v_exp_f32_e32 v17, v23
	s_nop 0
	v_add_f32_e32 v17, 1.0, v17
	v_rcp_f32_e32 v23, v17
	v_exp_f32_e32 v17, v20
	v_pk_mul_f32 v[12:13], v[18:19], v[22:23] op_sel_hi:[0,1]
	v_add_f32_e32 v17, 1.0, v17
	v_rcp_f32_e32 v20, v17
	v_exp_f32_e32 v17, v21
	v_pk_mul_f32 v[8:9], v[8:9], v[12:13]
	v_add_f32_e32 v17, 1.0, v17
	v_rcp_f32_e32 v21, v17
	v_cvt_pk_bf16_f32 v12, v9, s0
	v_cvt_pk_bf16_f32 v8, v8, s0
	v_pk_mul_f32 v[14:15], v[18:19], v[20:21] op_sel_hi:[0,1]
	v_pk_mul_f32 v[10:11], v[10:11], v[14:15]
	s_nop 0
	v_cvt_pk_bf16_f32 v9, v10, v11
	v_lshlrev_b32_e32 v10, 16, v12
	v_pk_mul_f32 v[12:13], v[4:5], v[16:17] op_sel_hi:[1,0]
	v_or_b32_sdwa v8, v10, v8 dst_sel:DWORD dst_unused:UNUSED_PAD src0_sel:DWORD src1_sel:WORD_0
	v_pk_mul_f32 v[10:11], v[6:7], v[16:17] op_sel_hi:[1,0]
	v_exp_f32_e32 v12, v12
	v_exp_f32_e32 v13, v13
	v_exp_f32_e32 v10, v10
	v_exp_f32_e32 v11, v11
	v_add_f32_e32 v12, 1.0, v12
	v_add_f32_e32 v13, 1.0, v13
	v_rcp_f32_e32 v12, v12
	v_rcp_f32_e32 v13, v13
	v_add_f32_e32 v10, 1.0, v10
	v_add_f32_e32 v11, 1.0, v11
	v_rcp_f32_e32 v10, v10
	v_rcp_f32_e32 v11, v11
	v_pk_mul_f32 v[4:5], v[18:19], v[12:13] op_sel_hi:[0,1]
	v_pk_mul_f32 v[0:1], v[0:1], v[4:5]
	v_pk_mul_f32 v[6:7], v[18:19], v[10:11] op_sel_hi:[0,1]
	v_pk_mul_f32 v[2:3], v[2:3], v[6:7]
	v_cvt_pk_bf16_f32 v10, v0, v1
	v_mad_i64_i32 v[0:1], s[0:1], v64, s9, v[112:113]
	v_cvt_pk_bf16_f32 v11, v2, v3
	v_lshl_add_u64 v[0:1], v[0:1], 0, v[114:115]
	s_mov_b32 s0, s10
	global_store_dwordx4 v[0:1], v[8:11], off
	s_cbranch_vccz .LBB0_399
	s_waitcnt vmcnt(0)
	s_cmpk_gt_u32 s25, 0xff
	s_cbranch_scc1 .LBB0_406
	s_barrier

.LBB0_1623:
	s_add_u32 s22, s20, 0x100
	s_addc_u32 s23, s21, 0
	s_add_i32 s46, 0, 0x10000
	v_add_u32_e32 v140, s46, v196
	ds_read_b128 v[128:131], v140
	ds_read_b128 v[132:135], v140 offset:1024
	ds_read_b128 v[136:139], v140 offset:2048
	ds_read_b128 v[140:143], v140 offset:3072
	s_cmp_eq_u32 s45, 40
	s_cselect_b32 s27, s7, s23
	s_cselect_b32 s26, s6, s22
	s_cselect_b32 s25, s9, s44
	s_cselect_b32 s24, s8, s33
	s_add_i32 m0, s34, 0xc000
	ds_read_b128 v[144:147], v198
	ds_read_b128 v[148:151], v198 offset:1024
	ds_read_b128 v[152:155], v198 offset:2048
	ds_read_b128 v[156:159], v198 offset:3072
	ds_read_b128 v[160:163], v198 offset:4096
	ds_read_b128 v[164:167], v198 offset:5120
	ds_read_b128 v[168:171], v198 offset:6144
	ds_read_b128 v[172:175], v198 offset:7168
	global_load_lds_dwordx4 v214, s[20:21]
	s_add_i32 m0, s34, 0xe000
	s_nop 0
	global_load_lds_dwordx4 v212, s[20:21]
	s_waitcnt lgkmcnt(8)
	s_barrier
	s_waitcnt lgkmcnt(0)
	s_setprio 1
	s_waitcnt lgkmcnt(0)
	v_mfma_f32_16x16x32_bf16 v[124:127], v[128:131], v[144:147], v[124:127]
	v_mfma_f32_16x16x32_bf16 v[120:123], v[136:139], v[144:147], v[120:123]
	v_mfma_f32_16x16x32_bf16 v[108:111], v[128:131], v[152:155], v[108:111]
	v_mfma_f32_16x16x32_bf16 v[104:107], v[136:139], v[152:155], v[104:107]
	v_mfma_f32_16x16x32_bf16 v[92:95], v[128:131], v[160:163], v[92:95]
	v_mfma_f32_16x16x32_bf16 v[88:91], v[136:139], v[160:163], v[88:91]
	v_mfma_f32_16x16x32_bf16 v[76:79], v[128:131], v[168:171], v[76:79]
	v_mfma_f32_16x16x32_bf16 v[72:75], v[136:139], v[168:171], v[72:75]
	v_mfma_f32_16x16x32_bf16 v[124:127], v[132:135], v[148:151], v[124:127]
	v_mfma_f32_16x16x32_bf16 v[120:123], v[140:143], v[148:151], v[120:123]
	v_mfma_f32_16x16x32_bf16 v[108:111], v[132:135], v[156:159], v[108:111]
	v_mfma_f32_16x16x32_bf16 v[104:107], v[140:143], v[156:159], v[104:107]
	v_mfma_f32_16x16x32_bf16 v[92:95], v[132:135], v[164:167], v[92:95]
	v_mfma_f32_16x16x32_bf16 v[88:91], v[140:143], v[164:167], v[88:91]
	v_mfma_f32_16x16x32_bf16 v[76:79], v[132:135], v[172:175], v[76:79]
	v_mfma_f32_16x16x32_bf16 v[72:75], v[140:143], v[172:175], v[72:75]
	s_setprio 0
	s_barrier
	s_add_i32 s47, 0, 0x14000
	s_add_i32 s20, s46, s31
	v_add_u32_e32 v188, s47, v196
	s_mov_b32 m0, s20
	ds_read_b128 v[176:179], v188
	ds_read_b128 v[180:183], v188 offset:1024
	ds_read_b128 v[184:187], v188 offset:2048
	ds_read_b128 v[188:191], v188 offset:3072
	global_load_lds_dwordx4 v192, s[24:25]
	s_add_i32 m0, s20, 0x2000
	s_nop 0
	global_load_lds_dwordx4 v210, s[24:25]
	s_barrier
	s_waitcnt lgkmcnt(0)
	s_setprio 1
	s_waitcnt lgkmcnt(0)
	v_mfma_f32_16x16x32_bf16 v[116:119], v[176:179], v[144:147], v[116:119]
	v_mfma_f32_16x16x32_bf16 v[112:115], v[184:187], v[144:147], v[112:115]
	v_mfma_f32_16x16x32_bf16 v[100:103], v[176:179], v[152:155], v[100:103]
	v_mfma_f32_16x16x32_bf16 v[96:99], v[184:187], v[152:155], v[96:99]
	v_mfma_f32_16x16x32_bf16 v[84:87], v[176:179], v[160:163], v[84:87]
	v_mfma_f32_16x16x32_bf16 v[80:83], v[184:187], v[160:163], v[80:83]
	v_mfma_f32_16x16x32_bf16 v[68:71], v[176:179], v[168:171], v[68:71]
	v_mfma_f32_16x16x32_bf16 v[64:67], v[184:187], v[168:171], v[64:67]
	v_mfma_f32_16x16x32_bf16 v[116:119], v[180:183], v[148:151], v[116:119]
	v_mfma_f32_16x16x32_bf16 v[112:115], v[188:191], v[148:151], v[112:115]
	v_mfma_f32_16x16x32_bf16 v[100:103], v[180:183], v[156:159], v[100:103]
	v_mfma_f32_16x16x32_bf16 v[96:99], v[188:191], v[156:159], v[96:99]
	v_mfma_f32_16x16x32_bf16 v[84:87], v[180:183], v[164:167], v[84:87]
	v_mfma_f32_16x16x32_bf16 v[80:83], v[188:191], v[164:167], v[80:83]
	v_mfma_f32_16x16x32_bf16 v[68:71], v[180:183], v[172:175], v[68:71]
	v_mfma_f32_16x16x32_bf16 v[64:67], v[188:191], v[172:175], v[64:67]
	s_setprio 0
	s_mov_b32 m0, s34
	s_add_u32 vcc_lo, s26, 0x80
	s_addc_u32 vcc_hi, s27, 0
	s_barrier
	ds_read_b128 v[144:147], v198 offset:16384
	ds_read_b128 v[148:151], v198 offset:17408
	ds_read_b128 v[152:155], v198 offset:18432
	ds_read_b128 v[156:159], v198 offset:19456
	ds_read_b128 v[160:163], v198 offset:20480
	ds_read_b128 v[164:167], v198 offset:21504
	ds_read_b128 v[168:171], v198 offset:22528
	ds_read_b128 v[172:175], v198 offset:23552
	global_load_lds_dwordx4 v206, s[26:27]
	s_mov_b32 m0, s35
	s_nop 0
	global_load_lds_dwordx4 v208, s[26:27]
	s_barrier
	s_waitcnt lgkmcnt(0)
	s_setprio 1
	s_waitcnt lgkmcnt(0)
	v_mfma_f32_16x16x32_bf16 v[60:63], v[128:131], v[144:147], v[60:63]
	v_mfma_f32_16x16x32_bf16 v[56:59], v[136:139], v[144:147], v[56:59]
	v_mfma_f32_16x16x32_bf16 v[44:47], v[128:131], v[152:155], v[44:47]
	v_mfma_f32_16x16x32_bf16 v[40:43], v[136:139], v[152:155], v[40:43]
	v_mfma_f32_16x16x32_bf16 v[28:31], v[128:131], v[160:163], v[28:31]
	v_mfma_f32_16x16x32_bf16 v[24:27], v[136:139], v[160:163], v[24:27]
	v_mfma_f32_16x16x32_bf16 v[12:15], v[128:131], v[168:171], v[12:15]
	v_mfma_f32_16x16x32_bf16 v[8:11], v[136:139], v[168:171], v[8:11]
	v_mfma_f32_16x16x32_bf16 v[60:63], v[132:135], v[148:151], v[60:63]
	v_mfma_f32_16x16x32_bf16 v[56:59], v[140:143], v[148:151], v[56:59]
	v_mfma_f32_16x16x32_bf16 v[44:47], v[132:135], v[156:159], v[44:47]
	v_mfma_f32_16x16x32_bf16 v[40:43], v[140:143], v[156:159], v[40:43]
	v_mfma_f32_16x16x32_bf16 v[28:31], v[132:135], v[164:167], v[28:31]
	v_mfma_f32_16x16x32_bf16 v[24:27], v[140:143], v[164:167], v[24:27]
	v_mfma_f32_16x16x32_bf16 v[12:15], v[132:135], v[172:175], v[12:15]
	v_mfma_f32_16x16x32_bf16 v[8:11], v[140:143], v[172:175], v[8:11]
	s_setprio 0
	s_barrier
	s_add_u32 s20, s24, 0xb0000
	s_addc_u32 s21, s25, 0
	s_add_i32 s46, s47, s31
	s_mov_b32 m0, s46
	s_nop 0
	global_load_lds_dwordx4 v192, s[20:21]
	s_add_i32 m0, s46, 0x2000
	s_nop 0
	global_load_lds_dwordx4 v210, s[20:21]
	s_waitcnt vmcnt(6)
	s_barrier
	s_setprio 1
	v_mfma_f32_16x16x32_bf16 v[52:55], v[176:179], v[144:147], v[52:55]
	v_mfma_f32_16x16x32_bf16 v[48:51], v[184:187], v[144:147], v[48:51]
	v_mfma_f32_16x16x32_bf16 v[36:39], v[176:179], v[152:155], v[36:39]
	v_mfma_f32_16x16x32_bf16 v[32:35], v[184:187], v[152:155], v[32:35]
	v_mfma_f32_16x16x32_bf16 v[20:23], v[176:179], v[160:163], v[20:23]
	v_mfma_f32_16x16x32_bf16 v[16:19], v[184:187], v[160:163], v[16:19]
	v_mfma_f32_16x16x32_bf16 v[4:7], v[176:179], v[168:171], v[4:7]
	v_mfma_f32_16x16x32_bf16 v[0:3], v[184:187], v[168:171], v[0:3]
	v_mfma_f32_16x16x32_bf16 v[52:55], v[180:183], v[148:151], v[52:55]
	v_mfma_f32_16x16x32_bf16 v[48:51], v[188:191], v[148:151], v[48:51]
	v_mfma_f32_16x16x32_bf16 v[36:39], v[180:183], v[156:159], v[36:39]
	v_mfma_f32_16x16x32_bf16 v[32:35], v[188:191], v[156:159], v[32:35]
	v_mfma_f32_16x16x32_bf16 v[20:23], v[180:183], v[164:167], v[20:23]
	v_mfma_f32_16x16x32_bf16 v[16:19], v[188:191], v[164:167], v[16:19]
	v_mfma_f32_16x16x32_bf16 v[4:7], v[180:183], v[172:175], v[4:7]
	v_mfma_f32_16x16x32_bf16 v[0:3], v[188:191], v[172:175], v[0:3]
	s_setprio 0
	s_add_i32 s46, 0, 0x18000
	v_add_u32_e32 v140, s46, v196
	s_barrier
	ds_read_b128 v[128:131], v140
	ds_read_b128 v[132:135], v140 offset:1024
	ds_read_b128 v[136:139], v140 offset:2048
	ds_read_b128 v[140:143], v140 offset:3072
	s_add_u32 s20, s26, 0xb0000
	s_addc_u32 s21, s27, 0
	s_mov_b32 m0, s36
	ds_read_b128 v[144:147], v198 offset:32768
	ds_read_b128 v[148:151], v198 offset:33792
	ds_read_b128 v[152:155], v198 offset:34816
	ds_read_b128 v[156:159], v198 offset:35840
	ds_read_b128 v[160:163], v198 offset:36864
	ds_read_b128 v[164:167], v198 offset:37888
	ds_read_b128 v[168:171], v198 offset:38912
	ds_read_b128 v[172:175], v198 offset:39936
	global_load_lds_dwordx4 v206, s[20:21]
	s_mov_b32 m0, s37
	s_nop 0
	global_load_lds_dwordx4 v208, s[20:21]
	s_waitcnt lgkmcnt(8)
	s_barrier
	s_waitcnt lgkmcnt(0)
	s_setprio 1
	s_waitcnt lgkmcnt(0)
	v_mfma_f32_16x16x32_bf16 v[124:127], v[128:131], v[144:147], v[124:127]
	v_mfma_f32_16x16x32_bf16 v[120:123], v[136:139], v[144:147], v[120:123]
	v_mfma_f32_16x16x32_bf16 v[108:111], v[128:131], v[152:155], v[108:111]
	v_mfma_f32_16x16x32_bf16 v[104:107], v[136:139], v[152:155], v[104:107]
	v_mfma_f32_16x16x32_bf16 v[92:95], v[128:131], v[160:163], v[92:95]
	v_mfma_f32_16x16x32_bf16 v[88:91], v[136:139], v[160:163], v[88:91]
	v_mfma_f32_16x16x32_bf16 v[76:79], v[128:131], v[168:171], v[76:79]
	v_mfma_f32_16x16x32_bf16 v[72:75], v[136:139], v[168:171], v[72:75]
	v_mfma_f32_16x16x32_bf16 v[124:127], v[132:135], v[148:151], v[124:127]
	v_mfma_f32_16x16x32_bf16 v[120:123], v[140:143], v[148:151], v[120:123]
	v_mfma_f32_16x16x32_bf16 v[108:111], v[132:135], v[156:159], v[108:111]
	v_mfma_f32_16x16x32_bf16 v[104:107], v[140:143], v[156:159], v[104:107]
	v_mfma_f32_16x16x32_bf16 v[92:95], v[132:135], v[164:167], v[92:95]
	v_mfma_f32_16x16x32_bf16 v[88:91], v[140:143], v[164:167], v[88:91]
	v_mfma_f32_16x16x32_bf16 v[76:79], v[132:135], v[172:175], v[76:79]
	v_mfma_f32_16x16x32_bf16 v[72:75], v[140:143], v[172:175], v[72:75]
	s_setprio 0
	s_barrier
	s_add_i32 s26, 0, 0x1c000
	s_add_i32 s20, s46, s31
	v_add_u32_e32 v188, s26, v196
	s_add_u32 s100, s24, 0x80
	s_addc_u32 s101, s25, 0
	s_mov_b32 m0, s20
	ds_read_b128 v[176:179], v188
	ds_read_b128 v[180:183], v188 offset:1024
	ds_read_b128 v[184:187], v188 offset:2048
	ds_read_b128 v[188:191], v188 offset:3072
	global_load_lds_dwordx4 v192, s[100:101]
	s_add_i32 m0, s20, 0x2000
	s_nop 0
	global_load_lds_dwordx4 v210, s[100:101]
	s_barrier
	s_waitcnt lgkmcnt(0)
	s_setprio 1
	s_waitcnt lgkmcnt(0)
	v_mfma_f32_16x16x32_bf16 v[116:119], v[176:179], v[144:147], v[116:119]
	v_mfma_f32_16x16x32_bf16 v[112:115], v[184:187], v[144:147], v[112:115]
	v_mfma_f32_16x16x32_bf16 v[100:103], v[176:179], v[152:155], v[100:103]
	v_mfma_f32_16x16x32_bf16 v[96:99], v[184:187], v[152:155], v[96:99]
	v_mfma_f32_16x16x32_bf16 v[84:87], v[176:179], v[160:163], v[84:87]
	v_mfma_f32_16x16x32_bf16 v[80:83], v[184:187], v[160:163], v[80:83]
	v_mfma_f32_16x16x32_bf16 v[68:71], v[176:179], v[168:171], v[68:71]
	v_mfma_f32_16x16x32_bf16 v[64:67], v[184:187], v[168:171], v[64:67]
	v_mfma_f32_16x16x32_bf16 v[116:119], v[180:183], v[148:151], v[116:119]
	v_mfma_f32_16x16x32_bf16 v[112:115], v[188:191], v[148:151], v[112:115]
	v_mfma_f32_16x16x32_bf16 v[100:103], v[180:183], v[156:159], v[100:103]
	v_mfma_f32_16x16x32_bf16 v[96:99], v[188:191], v[156:159], v[96:99]
	v_mfma_f32_16x16x32_bf16 v[84:87], v[180:183], v[164:167], v[84:87]
	v_mfma_f32_16x16x32_bf16 v[80:83], v[188:191], v[164:167], v[80:83]
	v_mfma_f32_16x16x32_bf16 v[68:71], v[180:183], v[172:175], v[68:71]
	v_mfma_f32_16x16x32_bf16 v[64:67], v[188:191], v[172:175], v[64:67]
	s_setprio 0
	s_mov_b32 m0, s38
	s_barrier
	ds_read_b128 v[144:147], v198 offset:49152
	ds_read_b128 v[148:151], v198 offset:50176
	ds_read_b128 v[152:155], v198 offset:51200
	ds_read_b128 v[156:159], v198 offset:52224
	ds_read_b128 v[160:163], v198 offset:53248
	ds_read_b128 v[164:167], v198 offset:54272
	ds_read_b128 v[168:171], v198 offset:55296
	ds_read_b128 v[172:175], v198 offset:56320
	global_load_lds_dwordx4 v206, vcc
	s_mov_b32 m0, s39
	s_nop 0
	global_load_lds_dwordx4 v208, vcc
	s_barrier
	s_waitcnt lgkmcnt(0)
	s_setprio 1
	s_waitcnt lgkmcnt(0)
	v_mfma_f32_16x16x32_bf16 v[60:63], v[128:131], v[144:147], v[60:63]
	v_mfma_f32_16x16x32_bf16 v[56:59], v[136:139], v[144:147], v[56:59]
	v_mfma_f32_16x16x32_bf16 v[44:47], v[128:131], v[152:155], v[44:47]
	v_mfma_f32_16x16x32_bf16 v[40:43], v[136:139], v[152:155], v[40:43]
	v_mfma_f32_16x16x32_bf16 v[28:31], v[128:131], v[160:163], v[28:31]
	v_mfma_f32_16x16x32_bf16 v[24:27], v[136:139], v[160:163], v[24:27]
	v_mfma_f32_16x16x32_bf16 v[12:15], v[128:131], v[168:171], v[12:15]
	v_mfma_f32_16x16x32_bf16 v[8:11], v[136:139], v[168:171], v[8:11]
	v_mfma_f32_16x16x32_bf16 v[60:63], v[132:135], v[148:151], v[60:63]
	v_mfma_f32_16x16x32_bf16 v[56:59], v[140:143], v[148:151], v[56:59]
	v_mfma_f32_16x16x32_bf16 v[44:47], v[132:135], v[156:159], v[44:47]
	v_mfma_f32_16x16x32_bf16 v[40:43], v[140:143], v[156:159], v[40:43]
	v_mfma_f32_16x16x32_bf16 v[28:31], v[132:135], v[164:167], v[28:31]
	v_mfma_f32_16x16x32_bf16 v[24:27], v[140:143], v[164:167], v[24:27]
	v_mfma_f32_16x16x32_bf16 v[12:15], v[132:135], v[172:175], v[12:15]
	v_mfma_f32_16x16x32_bf16 v[8:11], v[140:143], v[172:175], v[8:11]
	s_setprio 0
	s_barrier
	s_add_u32 s20, s24, 0xb0080
	s_addc_u32 s21, s25, 0
	s_add_i32 s24, s26, s31
	s_mov_b32 m0, s24
	s_nop 0
	global_load_lds_dwordx4 v192, s[20:21]
	s_add_i32 m0, s24, 0x2000
	s_nop 0
	global_load_lds_dwordx4 v210, s[20:21]
	s_waitcnt vmcnt(6)
	s_barrier
	s_setprio 1
	v_mfma_f32_16x16x32_bf16 v[52:55], v[176:179], v[144:147], v[52:55]
	v_mfma_f32_16x16x32_bf16 v[48:51], v[184:187], v[144:147], v[48:51]
	v_mfma_f32_16x16x32_bf16 v[36:39], v[176:179], v[152:155], v[36:39]
	v_mfma_f32_16x16x32_bf16 v[32:35], v[184:187], v[152:155], v[32:35]
	v_mfma_f32_16x16x32_bf16 v[20:23], v[176:179], v[160:163], v[20:23]
	v_mfma_f32_16x16x32_bf16 v[16:19], v[184:187], v[160:163], v[16:19]
	v_mfma_f32_16x16x32_bf16 v[4:7], v[176:179], v[168:171], v[4:7]
	v_mfma_f32_16x16x32_bf16 v[0:3], v[184:187], v[168:171], v[0:3]
	v_mfma_f32_16x16x32_bf16 v[52:55], v[180:183], v[148:151], v[52:55]
	v_mfma_f32_16x16x32_bf16 v[48:51], v[188:191], v[148:151], v[48:51]
	v_mfma_f32_16x16x32_bf16 v[36:39], v[180:183], v[156:159], v[36:39]
	v_mfma_f32_16x16x32_bf16 v[32:35], v[188:191], v[156:159], v[32:35]
	v_mfma_f32_16x16x32_bf16 v[20:23], v[180:183], v[164:167], v[20:23]
	v_mfma_f32_16x16x32_bf16 v[16:19], v[188:191], v[164:167], v[16:19]
	v_mfma_f32_16x16x32_bf16 v[4:7], v[180:183], v[172:175], v[4:7]
	v_mfma_f32_16x16x32_bf16 v[0:3], v[188:191], v[172:175], v[0:3]
	s_setprio 0
	s_add_i32 s45, s45, 2
	s_add_u32 s33, s33, 0x100
	s_addc_u32 s44, s44, 0
	s_cmp_gt_u32 s45, 41
	s_mov_b64 s[20:21], s[22:23]
	s_barrier
	s_cbranch_scc0 .LBB0_1623
	v_mov_b32_e32 v128, v252
	s_lshl_b32 s1, s1, 8
	v_readfirstlane_b32 s20, v128
	s_ashr_i32 s21, s20, 2
	s_andn2_b32 s21, s21, 63
	s_add_i32 s21, s21, s1
	s_lshr_b32 s1, s20, 1
	s_and_b32 s1, s1, 0x60
	s_lshl_b32 s0, s0, 8
	v_and_or_b32 v244, v128, 15, s21
	v_lshrrev_b32_e32 v128, 1, v128
	s_or_b32 s0, s1, s0
	v_and_b32_e32 v129, 64, v195
	v_and_or_b32 v216, v128, 24, s0
	v_xor_b32_e32 v128, 16, v195
	v_add_u32_e32 v129, 64, v129
	v_cmp_lt_i32_e32 vcc, v128, v129
	v_ashrrev_i32_e32 v245, 31, v244
	v_lshlrev_b64 v[220:221], 10, v[244:245]
	v_cndmask_b32_e32 v128, v195, v128, vcc
	v_lshlrev_b32_e32 v200, 2, v128
	v_xor_b32_e32 v128, 32, v195
	v_cmp_lt_i32_e32 vcc, v128, v129
	v_ashrrev_i32_e32 v217, 31, v216
	v_or_b32_e32 v218, 0x80, v216
	v_cndmask_b32_e32 v128, v195, v128, vcc
	v_lshlrev_b32_e32 v199, 2, v128
	v_lshl_add_u64 v[128:129], v[220:221], 0, v[216:217]
	v_lshlrev_b64 v[128:129], 1, v[128:129]
	v_lshl_add_u64 v[240:241], s[18:19], 0, v[128:129]
	v_lshl_add_u64 v[246:247], s[10:11], 0, v[128:129]
	global_load_dwordx4 v[188:191], v[240:241], off
	global_load_dwordx4 v[180:183], v[240:241], off offset:256
	global_load_dwordx4 v[184:187], v[246:247], off
	v_ashrrev_i32_e32 v219, 31, v218
	v_lshl_add_u64 v[128:129], v[220:221], 0, v[218:219]
	v_lshl_add_u64 v[242:243], v[128:129], 1, s[10:11]
	v_or_b32_e32 v128, 16, v244
	v_ashrrev_i32_e32 v129, 31, v128
	v_lshlrev_b64 v[128:129], 10, v[128:129]
	v_lshl_add_u64 v[130:131], v[128:129], 0, v[216:217]
	v_lshl_add_u64 v[128:129], v[128:129], 0, v[218:219]
	v_lshl_add_u64 v[236:237], v[128:129], 1, s[10:11]
	v_or_b32_e32 v128, 32, v244
	v_ashrrev_i32_e32 v129, 31, v128
	v_lshlrev_b64 v[130:131], 1, v[130:131]
	v_lshlrev_b64 v[128:129], 10, v[128:129]
	v_lshl_add_u64 v[234:235], s[18:19], 0, v[130:131]
	v_lshl_add_u64 v[238:239], s[10:11], 0, v[130:131]
	v_lshl_add_u64 v[130:131], v[128:129], 0, v[216:217]
	v_lshl_add_u64 v[128:129], v[128:129], 0, v[218:219]
	v_lshl_add_u64 v[230:231], v[128:129], 1, s[10:11]
	v_or_b32_e32 v128, 48, v244
	v_ashrrev_i32_e32 v129, 31, v128
	v_lshlrev_b64 v[130:131], 1, v[130:131]
	v_lshlrev_b64 v[128:129], 10, v[128:129]
	v_lshl_add_u64 v[226:227], s[18:19], 0, v[130:131]
	v_lshl_add_u64 v[232:233], s[10:11], 0, v[130:131]
	v_lshl_add_u64 v[130:131], v[128:129], 0, v[216:217]
	v_lshlrev_b64 v[130:131], 1, v[130:131]
	v_lshl_add_u64 v[132:133], v[128:129], 0, v[218:219]
	v_lshl_add_u64 v[222:223], s[18:19], 0, v[130:131]
	v_lshl_add_u64 v[228:229], s[10:11], 0, v[130:131]
	v_lshl_add_u64 v[224:225], v[132:133], 1, s[10:11]
	global_load_dwordx4 v[176:179], v[242:243], off
	global_load_dwordx4 v[172:175], v[234:235], off
	global_load_dwordx4 v[164:167], v[234:235], off offset:256
	global_load_dwordx4 v[168:171], v[238:239], off
	global_load_dwordx4 v[160:163], v[236:237], off
	global_load_dwordx4 v[156:159], v[226:227], off
	global_load_dwordx4 v[132:135], v[224:225], off
	global_load_dwordx4 v[152:155], v[232:233], off
	global_load_dwordx4 v[144:147], v[230:231], off
	global_load_dwordx4 v[148:151], v[226:227], off offset:256
	global_load_dwordx4 v[136:139], v[228:229], off
	global_load_dwordx4 v[140:143], v[222:223], off
	global_load_dwordx4 v[128:131], v[222:223], off offset:256
	v_cmp_gt_u32_e32 vcc, 16, v195
	s_waitcnt vmcnt(0)
	v_lshlrev_b32_e32 v248, 16, v188
	v_and_b32_e32 v249, 0xffff0000, v188
	v_lshlrev_b32_e32 v250, 16, v184
	v_and_b32_e32 v251, 0xffff0000, v184
	v_lshlrev_b32_e32 v188, 16, v189
	v_and_b32_e32 v189, 0xffff0000, v189
	v_lshlrev_b32_e32 v184, 16, v185
	v_and_b32_e32 v185, 0xffff0000, v185
	v_pk_add_f32 v[248:249], v[248:249], v[250:251]
	v_pk_add_f32 v[184:185], v[188:189], v[184:185]
	v_pk_fma_f32 v[188:189], v[124:125], 0.5, v[248:249] op_sel_hi:[1,0,1]
	v_pk_fma_f32 v[184:185], v[126:127], 0.5, v[184:185] op_sel_hi:[1,0,1]
	v_lshlrev_b32_e32 v124, 16, v190
	v_and_b32_e32 v125, 0xffff0000, v190
	v_lshlrev_b32_e32 v126, 16, v186
	v_and_b32_e32 v127, 0xffff0000, v186
	v_pk_add_f32 v[124:125], v[124:125], v[126:127]
	v_lshlrev_b32_e32 v126, 16, v191
	v_and_b32_e32 v127, 0xffff0000, v191
	v_lshlrev_b32_e32 v186, 16, v187
	v_and_b32_e32 v187, 0xffff0000, v187
	v_pk_add_f32 v[126:127], v[126:127], v[186:187]
	v_pk_fma_f32 v[190:191], v[120:121], 0.5, v[124:125] op_sel_hi:[1,0,1]
	v_cvt_pk_bf16_f32 v120, v188, v189
	v_pk_fma_f32 v[186:187], v[122:123], 0.5, v[126:127] op_sel_hi:[1,0,1]
	v_and_b32_e32 v123, 0xffff0000, v120
	v_lshlrev_b32_e32 v122, 16, v120
	v_pk_add_f32 v[122:123], v[188:189], v[122:123] neg_lo:[0,1] neg_hi:[0,1]
	v_cvt_pk_bf16_f32 v121, v184, v185
	v_cvt_pk_bf16_f32 v124, v122, v123
	v_and_b32_e32 v123, 0xffff0000, v121
	v_lshlrev_b32_e32 v122, 16, v121
	v_pk_add_f32 v[122:123], v[184:185], v[122:123] neg_lo:[0,1] neg_hi:[0,1]
	s_nop 0
	v_cvt_pk_bf16_f32 v125, v122, v123
	v_cvt_pk_bf16_f32 v122, v190, v191
	v_cvt_pk_bf16_f32 v123, v186, v187
	v_and_b32_e32 v127, 0xffff0000, v122
	v_lshlrev_b32_e32 v126, 16, v122
	v_and_b32_e32 v249, 0xffff0000, v123
	v_lshlrev_b32_e32 v248, 16, v123
	v_pk_add_f32 v[126:127], v[190:191], v[126:127] neg_lo:[0,1] neg_hi:[0,1]
	v_pk_add_f32 v[248:249], v[186:187], v[248:249] neg_lo:[0,1] neg_hi:[0,1]
	v_cvt_pk_bf16_f32 v126, v126, v127
	v_cvt_pk_bf16_f32 v127, v248, v249
	global_store_dwordx4 v[240:241], v[120:123], off
	global_store_dwordx4 v[246:247], v[124:127], off
	s_nop 0
	v_pk_mul_f32 v[122:123], v[190:191], v[190:191]
	v_pk_mul_f32 v[120:121], v[186:187], v[186:187]
	v_pk_fma_f32 v[122:123], v[188:189], v[188:189], v[122:123]
	v_pk_fma_f32 v[120:121], v[184:185], v[184:185], v[120:121]
	v_add_f32_e32 v122, v122, v123
	v_add_f32_e32 v120, v120, v122
	v_add_f32_e32 v120, v121, v120
	ds_bpermute_b32 v121, v200, v120
	v_lshl_add_u64 v[184:185], v[244:245], 2, s[14:15]
	s_waitcnt lgkmcnt(0)
	v_add_f32_e32 v120, v120, v121
	ds_bpermute_b32 v121, v199, v120
	s_and_saveexec_b64 s[20:21], vcc
	s_cbranch_execz .LBB0_1626
	s_waitcnt lgkmcnt(0)
	v_add_f32_e32 v120, v120, v121
	global_atomic_add_f32 v[184:185], v120, off

.LBB0_2804:
	s_add_u32 s20, s18, 0xfffc0080
	s_addc_u32 s21, s19, -1
	s_add_i32 s42, 0, 0x10000
	v_add_u32_e32 v150, s42, v151
	ds_read_b128 v[138:141], v150
	ds_read_b128 v[142:145], v150 offset:1024
	ds_read_b128 v[146:149], v150 offset:2048
	ds_read_b128 v[154:157], v150 offset:3072
	s_cmp_eq_u32 s41, 12
	s_cselect_b32 s23, s9, s21
	s_cselect_b32 s22, s33, s20
	s_cselect_b32 s21, s11, s40
	s_cselect_b32 s20, s38, s39
	s_add_i32 m0, s17, 0xc000
	ds_read_b128 v[158:161], v152
	ds_read_b128 v[162:165], v152 offset:1024
	ds_read_b128 v[166:169], v152 offset:2048
	ds_read_b128 v[170:173], v152 offset:3072
	ds_read_b128 v[174:177], v152 offset:4096
	ds_read_b128 v[178:181], v152 offset:5120
	ds_read_b128 v[182:185], v152 offset:6144
	ds_read_b128 v[186:189], v152 offset:7168
	global_load_lds_dwordx4 v136, s[18:19]
	s_add_i32 m0, s17, 0xe000
	s_nop 0
	global_load_lds_dwordx4 v134, s[18:19]
	s_waitcnt lgkmcnt(8)
	s_barrier
	s_waitcnt lgkmcnt(0)
	s_setprio 1
	s_waitcnt lgkmcnt(0)
	v_mfma_f32_16x16x32_bf16 v[124:127], v[138:141], v[158:161], v[124:127]
	v_mfma_f32_16x16x32_bf16 v[116:119], v[146:149], v[158:161], v[116:119]
	v_mfma_f32_16x16x32_bf16 v[108:111], v[138:141], v[166:169], v[108:111]
	v_mfma_f32_16x16x32_bf16 v[100:103], v[146:149], v[166:169], v[100:103]
	v_mfma_f32_16x16x32_bf16 v[92:95], v[138:141], v[174:177], v[92:95]
	v_mfma_f32_16x16x32_bf16 v[84:87], v[146:149], v[174:177], v[84:87]
	v_mfma_f32_16x16x32_bf16 v[76:79], v[138:141], v[182:185], v[76:79]
	v_mfma_f32_16x16x32_bf16 v[68:71], v[146:149], v[182:185], v[68:71]
	v_mfma_f32_16x16x32_bf16 v[124:127], v[142:145], v[162:165], v[124:127]
	v_mfma_f32_16x16x32_bf16 v[116:119], v[154:157], v[162:165], v[116:119]
	v_mfma_f32_16x16x32_bf16 v[108:111], v[142:145], v[170:173], v[108:111]
	v_mfma_f32_16x16x32_bf16 v[100:103], v[154:157], v[170:173], v[100:103]
	v_mfma_f32_16x16x32_bf16 v[92:95], v[142:145], v[178:181], v[92:95]
	v_mfma_f32_16x16x32_bf16 v[84:87], v[154:157], v[178:181], v[84:87]
	v_mfma_f32_16x16x32_bf16 v[76:79], v[142:145], v[186:189], v[76:79]
	v_mfma_f32_16x16x32_bf16 v[68:71], v[154:157], v[186:189], v[68:71]
	s_setprio 0
	s_barrier
	s_add_i32 s44, 0, 0x14000
	s_add_i32 s42, s42, s28
	v_add_u32_e32 v150, s44, v151
	s_mov_b32 m0, s42
	ds_read_b128 v[198:201], v150
	ds_read_b128 v[206:209], v150 offset:1024
	ds_read_b128 v[210:213], v150 offset:2048
	ds_read_b128 v[214:217], v150 offset:3072
	global_load_lds_dwordx4 v192, s[20:21]
	s_add_i32 m0, s42, 0x2000
	s_nop 0
	global_load_lds_dwordx4 v128, s[20:21]
	s_barrier
	s_waitcnt lgkmcnt(0)
	s_setprio 1
	s_waitcnt lgkmcnt(0)
	v_mfma_f32_16x16x32_bf16 v[120:123], v[198:201], v[158:161], v[120:123]
	v_mfma_f32_16x16x32_bf16 v[112:115], v[210:213], v[158:161], v[112:115]
	v_mfma_f32_16x16x32_bf16 v[104:107], v[198:201], v[166:169], v[104:107]
	v_mfma_f32_16x16x32_bf16 v[96:99], v[210:213], v[166:169], v[96:99]
	v_mfma_f32_16x16x32_bf16 v[88:91], v[198:201], v[174:177], v[88:91]
	v_mfma_f32_16x16x32_bf16 v[80:83], v[210:213], v[174:177], v[80:83]
	v_mfma_f32_16x16x32_bf16 v[72:75], v[198:201], v[182:185], v[72:75]
	v_mfma_f32_16x16x32_bf16 v[64:67], v[210:213], v[182:185], v[64:67]
	v_mfma_f32_16x16x32_bf16 v[120:123], v[206:209], v[162:165], v[120:123]
	v_mfma_f32_16x16x32_bf16 v[112:115], v[214:217], v[162:165], v[112:115]
	v_mfma_f32_16x16x32_bf16 v[104:107], v[206:209], v[170:173], v[104:107]
	v_mfma_f32_16x16x32_bf16 v[96:99], v[214:217], v[170:173], v[96:99]
	v_mfma_f32_16x16x32_bf16 v[88:91], v[206:209], v[178:181], v[88:91]
	v_mfma_f32_16x16x32_bf16 v[80:83], v[214:217], v[178:181], v[80:83]
	v_mfma_f32_16x16x32_bf16 v[72:75], v[206:209], v[186:189], v[72:75]
	v_mfma_f32_16x16x32_bf16 v[64:67], v[214:217], v[186:189], v[64:67]
	s_setprio 0
	s_mov_b32 m0, s17
	s_add_u32 vcc_lo, s22, 0x80
	s_addc_u32 vcc_hi, s23, 0
	s_barrier
	ds_read_b128 v[158:161], v152 offset:16384
	ds_read_b128 v[162:165], v152 offset:17408
	ds_read_b128 v[166:169], v152 offset:18432
	ds_read_b128 v[170:173], v152 offset:19456
	ds_read_b128 v[174:177], v152 offset:20480
	ds_read_b128 v[178:181], v152 offset:21504
	ds_read_b128 v[182:185], v152 offset:22528
	ds_read_b128 v[186:189], v152 offset:23552
	global_load_lds_dwordx4 v132, s[22:23]
	s_mov_b32 m0, s29
	s_nop 0
	global_load_lds_dwordx4 v130, s[22:23]
	s_barrier
	s_waitcnt lgkmcnt(0)
	s_setprio 1
	s_waitcnt lgkmcnt(0)
	v_mfma_f32_16x16x32_bf16 v[60:63], v[138:141], v[158:161], v[60:63]
	v_mfma_f32_16x16x32_bf16 v[52:55], v[146:149], v[158:161], v[52:55]
	v_mfma_f32_16x16x32_bf16 v[44:47], v[138:141], v[166:169], v[44:47]
	v_mfma_f32_16x16x32_bf16 v[36:39], v[146:149], v[166:169], v[36:39]
	v_mfma_f32_16x16x32_bf16 v[28:31], v[138:141], v[174:177], v[28:31]
	v_mfma_f32_16x16x32_bf16 v[20:23], v[146:149], v[174:177], v[20:23]
	v_mfma_f32_16x16x32_bf16 v[12:15], v[138:141], v[182:185], v[12:15]
	v_mfma_f32_16x16x32_bf16 v[4:7], v[146:149], v[182:185], v[4:7]
	v_mfma_f32_16x16x32_bf16 v[60:63], v[142:145], v[162:165], v[60:63]
	v_mfma_f32_16x16x32_bf16 v[52:55], v[154:157], v[162:165], v[52:55]
	v_mfma_f32_16x16x32_bf16 v[44:47], v[142:145], v[170:173], v[44:47]
	v_mfma_f32_16x16x32_bf16 v[36:39], v[154:157], v[170:173], v[36:39]
	v_mfma_f32_16x16x32_bf16 v[28:31], v[142:145], v[178:181], v[28:31]
	v_mfma_f32_16x16x32_bf16 v[20:23], v[154:157], v[178:181], v[20:23]
	v_mfma_f32_16x16x32_bf16 v[12:15], v[142:145], v[186:189], v[12:15]
	v_mfma_f32_16x16x32_bf16 v[4:7], v[154:157], v[186:189], v[4:7]
	s_setprio 0
	s_barrier
	s_add_u32 s42, s20, 0x40000
	s_addc_u32 s43, s21, 0
	s_add_i32 s44, s44, s28
	s_mov_b32 m0, s44
	s_nop 0
	global_load_lds_dwordx4 v192, s[42:43]
	s_add_i32 m0, s44, 0x2000
	s_nop 0
	global_load_lds_dwordx4 v128, s[42:43]
	s_waitcnt vmcnt(6)
	s_barrier
	s_setprio 1
	v_mfma_f32_16x16x32_bf16 v[56:59], v[198:201], v[158:161], v[56:59]
	v_mfma_f32_16x16x32_bf16 v[48:51], v[210:213], v[158:161], v[48:51]
	v_mfma_f32_16x16x32_bf16 v[40:43], v[198:201], v[166:169], v[40:43]
	v_mfma_f32_16x16x32_bf16 v[32:35], v[210:213], v[166:169], v[32:35]
	v_mfma_f32_16x16x32_bf16 v[24:27], v[198:201], v[174:177], v[24:27]
	v_mfma_f32_16x16x32_bf16 v[16:19], v[210:213], v[174:177], v[16:19]
	v_mfma_f32_16x16x32_bf16 v[8:11], v[198:201], v[182:185], v[8:11]
	v_mfma_f32_16x16x32_bf16 v[0:3], v[210:213], v[182:185], v[0:3]
	v_mfma_f32_16x16x32_bf16 v[56:59], v[206:209], v[162:165], v[56:59]
	v_mfma_f32_16x16x32_bf16 v[48:51], v[214:217], v[162:165], v[48:51]
	v_mfma_f32_16x16x32_bf16 v[40:43], v[206:209], v[170:173], v[40:43]
	v_mfma_f32_16x16x32_bf16 v[32:35], v[214:217], v[170:173], v[32:35]
	v_mfma_f32_16x16x32_bf16 v[24:27], v[206:209], v[178:181], v[24:27]
	v_mfma_f32_16x16x32_bf16 v[16:19], v[214:217], v[178:181], v[16:19]
	v_mfma_f32_16x16x32_bf16 v[8:11], v[206:209], v[186:189], v[8:11]
	v_mfma_f32_16x16x32_bf16 v[0:3], v[214:217], v[186:189], v[0:3]
	s_setprio 0
	s_add_i32 s42, 0, 0x18000
	v_add_u32_e32 v150, s42, v151
	s_barrier
	ds_read_b128 v[138:141], v150
	ds_read_b128 v[142:145], v150 offset:1024
	ds_read_b128 v[146:149], v150 offset:2048
	ds_read_b128 v[154:157], v150 offset:3072
	s_add_u32 s22, s22, 0x40000
	s_addc_u32 s23, s23, 0
	s_mov_b32 m0, s30
	ds_read_b128 v[158:161], v152 offset:32768
	ds_read_b128 v[162:165], v152 offset:33792
	ds_read_b128 v[166:169], v152 offset:34816
	ds_read_b128 v[170:173], v152 offset:35840
	ds_read_b128 v[174:177], v152 offset:36864
	ds_read_b128 v[178:181], v152 offset:37888
	ds_read_b128 v[182:185], v152 offset:38912
	ds_read_b128 v[186:189], v152 offset:39936
	global_load_lds_dwordx4 v132, s[22:23]
	s_mov_b32 m0, s31
	s_nop 0
	global_load_lds_dwordx4 v130, s[22:23]
	s_waitcnt lgkmcnt(8)
	s_barrier
	s_waitcnt lgkmcnt(0)
	s_setprio 1
	s_waitcnt lgkmcnt(0)
	v_mfma_f32_16x16x32_bf16 v[124:127], v[138:141], v[158:161], v[124:127]
	v_mfma_f32_16x16x32_bf16 v[116:119], v[146:149], v[158:161], v[116:119]
	v_mfma_f32_16x16x32_bf16 v[108:111], v[138:141], v[166:169], v[108:111]
	v_mfma_f32_16x16x32_bf16 v[100:103], v[146:149], v[166:169], v[100:103]
	v_mfma_f32_16x16x32_bf16 v[92:95], v[138:141], v[174:177], v[92:95]
	v_mfma_f32_16x16x32_bf16 v[84:87], v[146:149], v[174:177], v[84:87]
	v_mfma_f32_16x16x32_bf16 v[76:79], v[138:141], v[182:185], v[76:79]
	v_mfma_f32_16x16x32_bf16 v[68:71], v[146:149], v[182:185], v[68:71]
	v_mfma_f32_16x16x32_bf16 v[124:127], v[142:145], v[162:165], v[124:127]
	v_mfma_f32_16x16x32_bf16 v[116:119], v[154:157], v[162:165], v[116:119]
	v_mfma_f32_16x16x32_bf16 v[108:111], v[142:145], v[170:173], v[108:111]
	v_mfma_f32_16x16x32_bf16 v[100:103], v[154:157], v[170:173], v[100:103]
	v_mfma_f32_16x16x32_bf16 v[92:95], v[142:145], v[178:181], v[92:95]
	v_mfma_f32_16x16x32_bf16 v[84:87], v[154:157], v[178:181], v[84:87]
	v_mfma_f32_16x16x32_bf16 v[76:79], v[142:145], v[186:189], v[76:79]
	v_mfma_f32_16x16x32_bf16 v[68:71], v[154:157], v[186:189], v[68:71]
	s_setprio 0
	s_barrier
	s_add_i32 s22, 0, 0x1c000
	s_add_i32 s23, s42, s28
	v_add_u32_e32 v150, s22, v151
	s_add_u32 s100, s20, 0x80
	s_addc_u32 s101, s21, 0
	s_mov_b32 m0, s23
	ds_read_b128 v[198:201], v150
	ds_read_b128 v[206:209], v150 offset:1024
	ds_read_b128 v[210:213], v150 offset:2048
	ds_read_b128 v[214:217], v150 offset:3072
	global_load_lds_dwordx4 v192, s[100:101]
	s_add_i32 m0, s23, 0x2000
	s_nop 0
	global_load_lds_dwordx4 v128, s[100:101]
	s_barrier
	s_waitcnt lgkmcnt(0)
	s_setprio 1
	s_waitcnt lgkmcnt(0)
	v_mfma_f32_16x16x32_bf16 v[120:123], v[198:201], v[158:161], v[120:123]
	v_mfma_f32_16x16x32_bf16 v[112:115], v[210:213], v[158:161], v[112:115]
	v_mfma_f32_16x16x32_bf16 v[104:107], v[198:201], v[166:169], v[104:107]
	v_mfma_f32_16x16x32_bf16 v[96:99], v[210:213], v[166:169], v[96:99]
	v_mfma_f32_16x16x32_bf16 v[88:91], v[198:201], v[174:177], v[88:91]
	v_mfma_f32_16x16x32_bf16 v[80:83], v[210:213], v[174:177], v[80:83]
	v_mfma_f32_16x16x32_bf16 v[72:75], v[198:201], v[182:185], v[72:75]
	v_mfma_f32_16x16x32_bf16 v[64:67], v[210:213], v[182:185], v[64:67]
	v_mfma_f32_16x16x32_bf16 v[120:123], v[206:209], v[162:165], v[120:123]
	v_mfma_f32_16x16x32_bf16 v[112:115], v[214:217], v[162:165], v[112:115]
	v_mfma_f32_16x16x32_bf16 v[104:107], v[206:209], v[170:173], v[104:107]
	v_mfma_f32_16x16x32_bf16 v[96:99], v[214:217], v[170:173], v[96:99]
	v_mfma_f32_16x16x32_bf16 v[88:91], v[206:209], v[178:181], v[88:91]
	v_mfma_f32_16x16x32_bf16 v[80:83], v[214:217], v[178:181], v[80:83]
	v_mfma_f32_16x16x32_bf16 v[72:75], v[206:209], v[186:189], v[72:75]
	v_mfma_f32_16x16x32_bf16 v[64:67], v[214:217], v[186:189], v[64:67]
	s_setprio 0
	s_mov_b32 m0, s34
	s_barrier
	ds_read_b128 v[158:161], v152 offset:49152
	ds_read_b128 v[162:165], v152 offset:50176
	ds_read_b128 v[166:169], v152 offset:51200
	ds_read_b128 v[170:173], v152 offset:52224
	ds_read_b128 v[174:177], v152 offset:53248
	ds_read_b128 v[178:181], v152 offset:54272
	ds_read_b128 v[182:185], v152 offset:55296
	ds_read_b128 v[186:189], v152 offset:56320
	global_load_lds_dwordx4 v132, vcc
	s_mov_b32 m0, s35
	s_nop 0
	global_load_lds_dwordx4 v130, vcc
	s_barrier
	s_waitcnt lgkmcnt(0)
	s_setprio 1
	s_waitcnt lgkmcnt(0)
	v_mfma_f32_16x16x32_bf16 v[60:63], v[138:141], v[158:161], v[60:63]
	v_mfma_f32_16x16x32_bf16 v[52:55], v[146:149], v[158:161], v[52:55]
	v_mfma_f32_16x16x32_bf16 v[44:47], v[138:141], v[166:169], v[44:47]
	v_mfma_f32_16x16x32_bf16 v[36:39], v[146:149], v[166:169], v[36:39]
	v_mfma_f32_16x16x32_bf16 v[28:31], v[138:141], v[174:177], v[28:31]
	v_mfma_f32_16x16x32_bf16 v[20:23], v[146:149], v[174:177], v[20:23]
	v_mfma_f32_16x16x32_bf16 v[12:15], v[138:141], v[182:185], v[12:15]
	v_mfma_f32_16x16x32_bf16 v[4:7], v[146:149], v[182:185], v[4:7]
	v_mfma_f32_16x16x32_bf16 v[60:63], v[142:145], v[162:165], v[60:63]
	v_mfma_f32_16x16x32_bf16 v[52:55], v[154:157], v[162:165], v[52:55]
	v_mfma_f32_16x16x32_bf16 v[44:47], v[142:145], v[170:173], v[44:47]
	v_mfma_f32_16x16x32_bf16 v[36:39], v[154:157], v[170:173], v[36:39]
	v_mfma_f32_16x16x32_bf16 v[28:31], v[142:145], v[178:181], v[28:31]
	v_mfma_f32_16x16x32_bf16 v[20:23], v[154:157], v[178:181], v[20:23]
	v_mfma_f32_16x16x32_bf16 v[12:15], v[142:145], v[186:189], v[12:15]
	v_mfma_f32_16x16x32_bf16 v[4:7], v[154:157], v[186:189], v[4:7]
	s_setprio 0
	s_barrier
	s_add_u32 s20, s20, 0x40080
	s_addc_u32 s21, s21, 0
	s_add_i32 s22, s22, s28
	s_mov_b32 m0, s22
	s_nop 0
	global_load_lds_dwordx4 v192, s[20:21]
	s_add_i32 m0, s22, 0x2000
	s_nop 0
	global_load_lds_dwordx4 v128, s[20:21]
	s_waitcnt vmcnt(6)
	s_barrier
	s_setprio 1
	v_mfma_f32_16x16x32_bf16 v[56:59], v[198:201], v[158:161], v[56:59]
	v_mfma_f32_16x16x32_bf16 v[48:51], v[210:213], v[158:161], v[48:51]
	v_mfma_f32_16x16x32_bf16 v[40:43], v[198:201], v[166:169], v[40:43]
	v_mfma_f32_16x16x32_bf16 v[32:35], v[210:213], v[166:169], v[32:35]
	v_mfma_f32_16x16x32_bf16 v[24:27], v[198:201], v[174:177], v[24:27]
	v_mfma_f32_16x16x32_bf16 v[16:19], v[210:213], v[174:177], v[16:19]
	v_mfma_f32_16x16x32_bf16 v[8:11], v[198:201], v[182:185], v[8:11]
	v_mfma_f32_16x16x32_bf16 v[0:3], v[210:213], v[182:185], v[0:3]
	v_mfma_f32_16x16x32_bf16 v[56:59], v[206:209], v[162:165], v[56:59]
	v_mfma_f32_16x16x32_bf16 v[48:51], v[214:217], v[162:165], v[48:51]
	v_mfma_f32_16x16x32_bf16 v[40:43], v[206:209], v[170:173], v[40:43]
	v_mfma_f32_16x16x32_bf16 v[32:35], v[214:217], v[170:173], v[32:35]
	v_mfma_f32_16x16x32_bf16 v[24:27], v[206:209], v[178:181], v[24:27]
	v_mfma_f32_16x16x32_bf16 v[16:19], v[214:217], v[178:181], v[16:19]
	v_mfma_f32_16x16x32_bf16 v[8:11], v[206:209], v[186:189], v[8:11]
	v_mfma_f32_16x16x32_bf16 v[0:3], v[214:217], v[186:189], v[0:3]
	s_setprio 0
	s_add_i32 s41, s41, 2
	s_add_u32 s39, s39, 0x100
	s_addc_u32 s40, s40, 0
	s_add_u32 s18, s18, 0x100
	s_addc_u32 s19, s19, 0
	s_cmp_gt_u32 s41, 13
	s_barrier
	s_cbranch_scc0 .LBB0_2804
	v_mov_b32_e32 v139, v252
	s_lshl_b32 s11, s16, 8
	v_readfirstlane_b32 s9, v139
	s_ashr_i32 s16, s9, 2
	s_andn2_b32 s16, s16, 63
	s_lshr_b32 s9, s9, 1
	s_add_i32 s16, s16, s11
	s_lshl_b32 s11, s37, 7
	s_and_b32 s9, s9, 0x60
	v_and_or_b32 v138, v139, 15, s16
	s_or_b32 s9, s9, s11
	v_lshrrev_b32_e32 v139, 1, v139
	v_and_or_b32 v148, v139, 24, s9
	v_ashrrev_i32_e32 v139, 31, v138
	v_lshl_add_u64 v[140:141], v[138:139], 2, s[6:7]
	v_or_b32_e32 v146, 16, v138
	v_ashrrev_i32_e32 v147, 31, v146
	v_lshl_add_u64 v[142:143], v[146:147], 2, s[6:7]
	v_or_b32_e32 v144, 32, v138
	v_ashrrev_i32_e32 v145, 31, v144
	v_lshl_add_u64 v[142:143], v[144:145], 2, s[6:7]
	v_or_b32_e32 v142, 48, v138
	v_ashrrev_i32_e32 v143, 31, v142
	v_lshl_add_u64 v[154:155], v[142:143], 2, s[6:7]
	v_pk_mul_f32 v[120:121], v[124:125], v[120:121]
	v_pk_mul_f32 v[122:123], v[126:127], v[122:123]
	v_pk_mul_f32 v[112:113], v[116:117], v[112:113]
	v_pk_mul_f32 v[114:115], v[118:119], v[114:115]
	v_ashrrev_i32_e32 v149, 31, v148
	s_movk_i32 s9, 0x1600
	v_pk_mul_f32 v[104:105], v[108:109], v[104:105]
	v_pk_mul_f32 v[106:107], v[110:111], v[106:107]
	v_pk_mul_f32 v[96:97], v[100:101], v[96:97]
	v_pk_mul_f32 v[98:99], v[102:103], v[98:99]
	v_pk_mul_f32 v[88:89], v[92:93], v[88:89]
	v_pk_mul_f32 v[90:91], v[94:95], v[90:91]
	v_pk_mul_f32 v[80:81], v[84:85], v[80:81]
	v_pk_mul_f32 v[82:83], v[86:87], v[82:83]
	v_pk_mul_f32 v[72:73], v[76:77], v[72:73]
	v_pk_mul_f32 v[74:75], v[78:79], v[74:75]
	v_pk_mul_f32 v[64:65], v[68:69], v[64:65]
	v_pk_mul_f32 v[66:67], v[70:71], v[66:67]
	v_pk_mul_f32 v[56:57], v[60:61], v[56:57]
	v_pk_mul_f32 v[58:59], v[62:63], v[58:59]
	v_pk_mul_f32 v[48:49], v[52:53], v[48:49]
	v_pk_mul_f32 v[50:51], v[54:55], v[50:51]
	v_pk_mul_f32 v[40:41], v[44:45], v[40:41]
	v_pk_mul_f32 v[42:43], v[46:47], v[42:43]
	v_pk_mul_f32 v[32:33], v[36:37], v[32:33]
	v_pk_mul_f32 v[34:35], v[38:39], v[34:35]
	v_pk_mul_f32 v[24:25], v[28:29], v[24:25]
	v_pk_mul_f32 v[26:27], v[30:31], v[26:27]
	v_pk_mul_f32 v[16:17], v[20:21], v[16:17]
	v_pk_mul_f32 v[18:19], v[22:23], v[18:19]
	v_pk_mul_f32 v[8:9], v[12:13], v[8:9]
	v_pk_mul_f32 v[10:11], v[14:15], v[10:11]
	v_pk_mul_f32 v[0:1], v[4:5], v[0:1]
	v_pk_mul_f32 v[2:3], v[6:7], v[2:3]
	s_mov_b32 s37, s10
	s_mov_b32 s16, s8
	s_mov_b64 s[20:21], s[12:13]
	v_fmamk_f32 v143, v231, 0x3a800000, v194
	v_cmp_gt_f32_e32 vcc, s2, v143
	v_mul_f32_e32 v150, 0x4b800000, v143
	s_nop 0
	v_cndmask_b32_e32 v143, v143, v150, vcc
	v_rsq_f32_e32 v143, v143
	s_nop 0
	v_mul_f32_e32 v150, 0x45800000, v143
	v_cndmask_b32_e32 v143, v143, v150, vcc
	v_mul_f32_e32 v154, 0xbfb8aa3b, v143
	v_pk_mul_f32 v[158:159], v[124:125], v[154:155] op_sel_hi:[1,0]
	v_mul_f32_e32 v150, v143, v143
	v_exp_f32_e32 v143, v158
	v_pk_mul_f32 v[156:157], v[126:127], v[154:155] op_sel_hi:[1,0]
	v_add_f32_e32 v143, 1.0, v143
	v_rcp_f32_e32 v158, v143
	v_exp_f32_e32 v143, v159
	s_nop 0
	v_add_f32_e32 v143, 1.0, v143
	v_rcp_f32_e32 v159, v143
	v_exp_f32_e32 v143, v156
	v_pk_mul_f32 v[124:125], v[150:151], v[158:159] op_sel_hi:[0,1]
	v_add_f32_e32 v143, 1.0, v143
	v_rcp_f32_e32 v156, v143
	v_exp_f32_e32 v143, v157
	v_pk_mul_f32 v[120:121], v[120:121], v[124:125]
	v_add_f32_e32 v143, 1.0, v143
	v_rcp_f32_e32 v157, v143
	v_cvt_pk_bf16_f32 v124, v121, s0
	v_cvt_pk_bf16_f32 v120, v120, s0
	v_pk_mul_f32 v[126:127], v[150:151], v[156:157] op_sel_hi:[0,1]
	v_pk_mul_f32 v[122:123], v[122:123], v[126:127]
	s_nop 0
	v_cvt_pk_bf16_f32 v121, v122, v123
	v_lshlrev_b32_e32 v122, 16, v124
	v_pk_mul_f32 v[124:125], v[116:117], v[154:155] op_sel_hi:[1,0]
	v_or_b32_sdwa v120, v122, v120 dst_sel:DWORD dst_unused:UNUSED_PAD src0_sel:DWORD src1_sel:WORD_0
	v_pk_mul_f32 v[122:123], v[118:119], v[154:155] op_sel_hi:[1,0]
	v_exp_f32_e32 v124, v124
	v_exp_f32_e32 v125, v125
	v_exp_f32_e32 v122, v122
	v_exp_f32_e32 v123, v123
	v_add_f32_e32 v124, 1.0, v124
	v_add_f32_e32 v125, 1.0, v125
	v_rcp_f32_e32 v124, v124
	v_rcp_f32_e32 v125, v125
	v_add_f32_e32 v122, 1.0, v122
	v_add_f32_e32 v123, 1.0, v123
	v_rcp_f32_e32 v122, v122
	v_rcp_f32_e32 v123, v123
	v_pk_mul_f32 v[116:117], v[150:151], v[124:125] op_sel_hi:[0,1]
	v_pk_mul_f32 v[112:113], v[112:113], v[116:117]
	v_pk_mul_f32 v[118:119], v[150:151], v[122:123] op_sel_hi:[0,1]
	v_pk_mul_f32 v[114:115], v[114:115], v[118:119]
	v_cvt_pk_bf16_f32 v122, v112, v113
	v_mov_b64_e32 v[112:113], s[4:5]
	v_cvt_pk_bf16_f32 v123, v114, v115
	v_mad_i64_i32 v[116:117], s[18:19], v138, s9, v[112:113]
	v_lshlrev_b64 v[114:115], 1, v[148:149]
	v_lshl_add_u64 v[116:117], v[116:117], 0, v[114:115]
	global_store_dwordx4 v[116:117], v[120:123], off
	v_fmamk_f32 v116, v232, 0x3a800000, v194
	v_cmp_gt_f32_e32 vcc, s2, v116
	v_mul_f32_e32 v117, 0x4b800000, v116
	s_nop 0
	v_cndmask_b32_e32 v116, v116, v117, vcc
	v_rsq_f32_e32 v116, v116
	s_nop 0
	v_mul_f32_e32 v117, 0x45800000, v116
	v_cndmask_b32_e32 v116, v116, v117, vcc
	v_mul_f32_e32 v118, 0xbfb8aa3b, v116
	v_pk_mul_f32 v[122:123], v[108:109], v[118:119] op_sel_hi:[1,0]
	v_pk_mul_f32 v[120:121], v[110:111], v[118:119] op_sel_hi:[1,0]
	v_exp_f32_e32 v117, v122
	v_mul_f32_e32 v116, v116, v116
	v_add_f32_e32 v117, 1.0, v117
	v_rcp_f32_e32 v122, v117
	v_exp_f32_e32 v117, v123
	s_nop 0
	v_add_f32_e32 v117, 1.0, v117
	v_rcp_f32_e32 v123, v117
	v_exp_f32_e32 v117, v120
	s_nop 0
	v_add_f32_e32 v117, 1.0, v117
	v_rcp_f32_e32 v120, v117
	v_exp_f32_e32 v117, v121
	s_nop 0
	v_add_f32_e32 v117, 1.0, v117
	v_rcp_f32_e32 v121, v117
	v_pk_mul_f32 v[108:109], v[116:117], v[122:123] op_sel_hi:[0,1]
	v_pk_mul_f32 v[104:105], v[104:105], v[108:109]
	v_pk_mul_f32 v[110:111], v[116:117], v[120:121] op_sel_hi:[0,1]
	v_pk_mul_f32 v[106:107], v[106:107], v[110:111]
	v_cvt_pk_bf16_f32 v108, v105, s0
	v_cvt_pk_bf16_f32 v104, v104, s0
	v_cvt_pk_bf16_f32 v105, v106, v107
	v_lshlrev_b32_e32 v106, 16, v108
	v_pk_mul_f32 v[108:109], v[100:101], v[118:119] op_sel_hi:[1,0]
	v_or_b32_sdwa v104, v106, v104 dst_sel:DWORD dst_unused:UNUSED_PAD src0_sel:DWORD src1_sel:WORD_0
	v_pk_mul_f32 v[106:107], v[102:103], v[118:119] op_sel_hi:[1,0]
	v_exp_f32_e32 v108, v108
	v_exp_f32_e32 v109, v109
	v_exp_f32_e32 v106, v106
	v_exp_f32_e32 v107, v107
	v_add_f32_e32 v108, 1.0, v108
	v_add_f32_e32 v109, 1.0, v109
	v_rcp_f32_e32 v108, v108
	v_rcp_f32_e32 v109, v109
	v_add_f32_e32 v106, 1.0, v106
	v_add_f32_e32 v107, 1.0, v107
	v_rcp_f32_e32 v106, v106
	v_rcp_f32_e32 v107, v107
	v_pk_mul_f32 v[100:101], v[116:117], v[108:109] op_sel_hi:[0,1]
	v_pk_mul_f32 v[96:97], v[96:97], v[100:101]
	v_pk_mul_f32 v[102:103], v[116:117], v[106:107] op_sel_hi:[0,1]
	v_pk_mul_f32 v[98:99], v[98:99], v[102:103]
	v_cvt_pk_bf16_f32 v106, v96, v97
	v_mad_i64_i32 v[96:97], s[18:19], v146, s9, v[112:113]
	v_cvt_pk_bf16_f32 v107, v98, v99
	v_lshl_add_u64 v[96:97], v[96:97], 0, v[114:115]
	global_store_dwordx4 v[96:97], v[104:107], off
	v_fmamk_f32 v96, v233, 0x3a800000, v194
	v_cmp_gt_f32_e32 vcc, s2, v96
	v_mul_f32_e32 v97, 0x4b800000, v96
	s_nop 0
	v_cndmask_b32_e32 v96, v96, v97, vcc
	v_rsq_f32_e32 v96, v96
	s_nop 0
	v_mul_f32_e32 v97, 0x45800000, v96
	v_cndmask_b32_e32 v97, v96, v97, vcc
	v_mul_f32_e32 v96, 0xbfb8aa3b, v97
	v_pk_mul_f32 v[102:103], v[92:93], v[96:97] op_sel_hi:[1,0]
	v_mul_f32_e32 v98, v97, v97
	v_pk_mul_f32 v[100:101], v[94:95], v[96:97] op_sel_hi:[1,0]
	v_exp_f32_e32 v97, v102
	s_nop 0
	v_add_f32_e32 v97, 1.0, v97
	v_rcp_f32_e32 v102, v97
	v_exp_f32_e32 v97, v103
	s_nop 0
	v_add_f32_e32 v97, 1.0, v97
	v_rcp_f32_e32 v103, v97
	v_exp_f32_e32 v97, v100
	v_pk_mul_f32 v[92:93], v[98:99], v[102:103] op_sel_hi:[0,1]
	v_add_f32_e32 v97, 1.0, v97
	v_rcp_f32_e32 v100, v97
	v_exp_f32_e32 v97, v101
	v_pk_mul_f32 v[88:89], v[88:89], v[92:93]
	v_add_f32_e32 v97, 1.0, v97
	v_rcp_f32_e32 v101, v97
	v_cvt_pk_bf16_f32 v92, v89, s0
	v_cvt_pk_bf16_f32 v88, v88, s0
	v_pk_mul_f32 v[94:95], v[98:99], v[100:101] op_sel_hi:[0,1]
	v_pk_mul_f32 v[90:91], v[90:91], v[94:95]
	s_nop 0
	v_cvt_pk_bf16_f32 v89, v90, v91
	v_lshlrev_b32_e32 v90, 16, v92
	v_pk_mul_f32 v[92:93], v[84:85], v[96:97] op_sel_hi:[1,0]
	v_or_b32_sdwa v88, v90, v88 dst_sel:DWORD dst_unused:UNUSED_PAD src0_sel:DWORD src1_sel:WORD_0
	v_pk_mul_f32 v[90:91], v[86:87], v[96:97] op_sel_hi:[1,0]
	v_exp_f32_e32 v92, v92
	v_exp_f32_e32 v93, v93
	v_exp_f32_e32 v90, v90
	v_exp_f32_e32 v91, v91
	v_add_f32_e32 v92, 1.0, v92
	v_add_f32_e32 v93, 1.0, v93
	v_rcp_f32_e32 v92, v92
	v_rcp_f32_e32 v93, v93
	v_add_f32_e32 v90, 1.0, v90
	v_add_f32_e32 v91, 1.0, v91
	v_rcp_f32_e32 v90, v90
	v_rcp_f32_e32 v91, v91
	v_pk_mul_f32 v[84:85], v[98:99], v[92:93] op_sel_hi:[0,1]
	v_pk_mul_f32 v[80:81], v[80:81], v[84:85]
	v_pk_mul_f32 v[86:87], v[98:99], v[90:91] op_sel_hi:[0,1]
	v_pk_mul_f32 v[82:83], v[82:83], v[86:87]
	v_cvt_pk_bf16_f32 v90, v80, v81
	v_mad_i64_i32 v[80:81], s[18:19], v144, s9, v[112:113]
	v_cvt_pk_bf16_f32 v91, v82, v83
	v_lshl_add_u64 v[80:81], v[80:81], 0, v[114:115]
	global_store_dwordx4 v[80:81], v[88:91], off
	v_fmamk_f32 v80, v234, 0x3a800000, v194
	v_cmp_gt_f32_e32 vcc, s2, v80
	v_mul_f32_e32 v81, 0x4b800000, v80
	s_nop 0
	v_cndmask_b32_e32 v80, v80, v81, vcc
	v_rsq_f32_e32 v80, v80
	s_nop 0
	v_mul_f32_e32 v81, 0x45800000, v80
	v_cndmask_b32_e32 v81, v80, v81, vcc
	v_mul_f32_e32 v80, 0xbfb8aa3b, v81
	v_pk_mul_f32 v[86:87], v[76:77], v[80:81] op_sel_hi:[1,0]
	v_mul_f32_e32 v82, v81, v81
	v_pk_mul_f32 v[84:85], v[78:79], v[80:81] op_sel_hi:[1,0]
	v_exp_f32_e32 v81, v86
	s_nop 0
	v_add_f32_e32 v81, 1.0, v81
	v_rcp_f32_e32 v86, v81
	v_exp_f32_e32 v81, v87
	s_nop 0
	v_add_f32_e32 v81, 1.0, v81
	v_rcp_f32_e32 v87, v81
	v_exp_f32_e32 v81, v84
	v_pk_mul_f32 v[76:77], v[82:83], v[86:87] op_sel_hi:[0,1]
	v_add_f32_e32 v81, 1.0, v81
	v_rcp_f32_e32 v84, v81
	v_exp_f32_e32 v81, v85
	v_pk_mul_f32 v[72:73], v[72:73], v[76:77]
	v_add_f32_e32 v81, 1.0, v81
	v_rcp_f32_e32 v85, v81
	v_cvt_pk_bf16_f32 v76, v73, s0
	v_cvt_pk_bf16_f32 v72, v72, s0
	v_pk_mul_f32 v[78:79], v[82:83], v[84:85] op_sel_hi:[0,1]
	v_pk_mul_f32 v[74:75], v[74:75], v[78:79]
	s_nop 0
	v_cvt_pk_bf16_f32 v73, v74, v75
	v_lshlrev_b32_e32 v74, 16, v76
	v_pk_mul_f32 v[76:77], v[68:69], v[80:81] op_sel_hi:[1,0]
	v_or_b32_sdwa v72, v74, v72 dst_sel:DWORD dst_unused:UNUSED_PAD src0_sel:DWORD src1_sel:WORD_0
	v_pk_mul_f32 v[74:75], v[70:71], v[80:81] op_sel_hi:[1,0]
	v_exp_f32_e32 v76, v76
	v_exp_f32_e32 v77, v77
	v_exp_f32_e32 v74, v74
	v_exp_f32_e32 v75, v75
	v_add_f32_e32 v76, 1.0, v76
	v_add_f32_e32 v77, 1.0, v77
	v_rcp_f32_e32 v76, v76
	v_rcp_f32_e32 v77, v77
	v_add_f32_e32 v74, 1.0, v74
	v_add_f32_e32 v75, 1.0, v75
	v_rcp_f32_e32 v74, v74
	v_rcp_f32_e32 v75, v75
	v_pk_mul_f32 v[68:69], v[82:83], v[76:77] op_sel_hi:[0,1]
	v_pk_mul_f32 v[64:65], v[64:65], v[68:69]
	v_add_u32_e32 v69, 0x90, v138
	v_pk_mul_f32 v[70:71], v[82:83], v[74:75] op_sel_hi:[0,1]
	v_pk_mul_f32 v[66:67], v[66:67], v[70:71]
	v_cvt_pk_bf16_f32 v74, v64, v65
	v_mad_i64_i32 v[64:65], s[18:19], v142, s9, v[112:113]
	v_cvt_pk_bf16_f32 v75, v66, v67
	v_lshl_add_u64 v[64:65], v[64:65], 0, v[114:115]
	global_store_dwordx4 v[64:65], v[72:75], off
	v_add_u32_e32 v67, 0x80, v138
	v_add_u32_e32 v66, 0xa0, v138
	v_add_u32_e32 v64, 0xb0, v138
	v_fmamk_f32 v68, v235, 0x3a800000, v194
	v_cmp_gt_f32_e32 vcc, s2, v68
	v_mul_f32_e32 v70, 0x4b800000, v68
	s_nop 0
	v_cndmask_b32_e32 v68, v68, v70, vcc
	v_rsq_f32_e32 v68, v68
	s_nop 0
	v_mul_f32_e32 v70, 0x45800000, v68
	v_cndmask_b32_e32 v70, v68, v70, vcc
	v_mul_f32_e32 v68, 0xbfb8aa3b, v70
	v_pk_mul_f32 v[74:75], v[60:61], v[68:69] op_sel_hi:[1,0]
	v_pk_mul_f32 v[72:73], v[62:63], v[68:69] op_sel_hi:[1,0]
	v_exp_f32_e32 v74, v74
	v_exp_f32_e32 v75, v75
	v_exp_f32_e32 v72, v72
	v_exp_f32_e32 v73, v73
	v_add_f32_e32 v74, 1.0, v74
	v_add_f32_e32 v75, 1.0, v75
	v_rcp_f32_e32 v74, v74
	v_rcp_f32_e32 v75, v75
	v_add_f32_e32 v72, 1.0, v72
	v_add_f32_e32 v73, 1.0, v73
	v_rcp_f32_e32 v72, v72
	v_rcp_f32_e32 v73, v73
	v_mul_f32_e32 v70, v70, v70
	v_pk_mul_f32 v[60:61], v[70:71], v[74:75] op_sel_hi:[0,1]
	v_pk_mul_f32 v[56:57], v[56:57], v[60:61]
	v_pk_mul_f32 v[62:63], v[70:71], v[72:73] op_sel_hi:[0,1]
	v_pk_mul_f32 v[58:59], v[58:59], v[62:63]
	v_cvt_pk_bf16_f32 v60, v57, s0
	v_cvt_pk_bf16_f32 v56, v56, s0
	v_cvt_pk_bf16_f32 v57, v58, v59
	v_lshlrev_b32_e32 v58, 16, v60
	v_pk_mul_f32 v[60:61], v[52:53], v[68:69] op_sel_hi:[1,0]
	v_or_b32_sdwa v56, v58, v56 dst_sel:DWORD dst_unused:UNUSED_PAD src0_sel:DWORD src1_sel:WORD_0
	v_pk_mul_f32 v[58:59], v[54:55], v[68:69] op_sel_hi:[1,0]
	v_exp_f32_e32 v60, v60
	v_exp_f32_e32 v61, v61
	v_exp_f32_e32 v58, v58
	v_exp_f32_e32 v59, v59
	v_add_f32_e32 v60, 1.0, v60
	v_add_f32_e32 v61, 1.0, v61
	v_rcp_f32_e32 v60, v60
	v_rcp_f32_e32 v61, v61
	v_add_f32_e32 v58, 1.0, v58
	v_add_f32_e32 v59, 1.0, v59
	v_rcp_f32_e32 v58, v58
	v_rcp_f32_e32 v59, v59
	v_pk_mul_f32 v[52:53], v[70:71], v[60:61] op_sel_hi:[0,1]
	v_pk_mul_f32 v[48:49], v[48:49], v[52:53]
	v_pk_mul_f32 v[54:55], v[70:71], v[58:59] op_sel_hi:[0,1]
	v_pk_mul_f32 v[50:51], v[50:51], v[54:55]
	v_cvt_pk_bf16_f32 v58, v48, v49
	v_mad_i64_i32 v[48:49], s[18:19], v67, s9, v[112:113]
	v_cvt_pk_bf16_f32 v59, v50, v51
	v_lshl_add_u64 v[48:49], v[48:49], 0, v[114:115]
	global_store_dwordx4 v[48:49], v[56:59], off
	v_fmamk_f32 v48, v236, 0x3a800000, v194
	v_cmp_gt_f32_e32 vcc, s2, v48
	v_mul_f32_e32 v49, 0x4b800000, v48
	s_nop 0
	v_cndmask_b32_e32 v48, v48, v49, vcc
	v_rsq_f32_e32 v48, v48
	s_nop 0
	v_mul_f32_e32 v49, 0x45800000, v48
	v_cndmask_b32_e32 v49, v48, v49, vcc
	v_mul_f32_e32 v48, 0xbfb8aa3b, v49
	v_pk_mul_f32 v[54:55], v[44:45], v[48:49] op_sel_hi:[1,0]
	v_mul_f32_e32 v50, v49, v49
	v_pk_mul_f32 v[52:53], v[46:47], v[48:49] op_sel_hi:[1,0]
	v_exp_f32_e32 v49, v54
	s_nop 0
	v_add_f32_e32 v49, 1.0, v49
	v_rcp_f32_e32 v54, v49
	v_exp_f32_e32 v49, v55
	s_nop 0
	v_add_f32_e32 v49, 1.0, v49
	v_rcp_f32_e32 v55, v49
	v_exp_f32_e32 v49, v52
	v_pk_mul_f32 v[44:45], v[50:51], v[54:55] op_sel_hi:[0,1]
	v_add_f32_e32 v49, 1.0, v49
	v_rcp_f32_e32 v52, v49
	v_exp_f32_e32 v49, v53
	v_pk_mul_f32 v[40:41], v[40:41], v[44:45]
	v_add_f32_e32 v49, 1.0, v49
	v_rcp_f32_e32 v53, v49
	v_cvt_pk_bf16_f32 v44, v41, s0
	v_cvt_pk_bf16_f32 v40, v40, s0
	v_pk_mul_f32 v[46:47], v[50:51], v[52:53] op_sel_hi:[0,1]
	v_pk_mul_f32 v[42:43], v[42:43], v[46:47]
	s_nop 0
	v_cvt_pk_bf16_f32 v41, v42, v43
	v_lshlrev_b32_e32 v42, 16, v44
	v_pk_mul_f32 v[44:45], v[36:37], v[48:49] op_sel_hi:[1,0]
	v_or_b32_sdwa v40, v42, v40 dst_sel:DWORD dst_unused:UNUSED_PAD src0_sel:DWORD src1_sel:WORD_0
	v_pk_mul_f32 v[42:43], v[38:39], v[48:49] op_sel_hi:[1,0]
	v_exp_f32_e32 v44, v44
	v_exp_f32_e32 v45, v45
	v_exp_f32_e32 v42, v42
	v_exp_f32_e32 v43, v43
	v_add_f32_e32 v44, 1.0, v44
	v_add_f32_e32 v45, 1.0, v45
	v_rcp_f32_e32 v44, v44
	v_rcp_f32_e32 v45, v45
	v_add_f32_e32 v42, 1.0, v42
	v_add_f32_e32 v43, 1.0, v43
	v_rcp_f32_e32 v42, v42
	v_rcp_f32_e32 v43, v43
	v_pk_mul_f32 v[36:37], v[50:51], v[44:45] op_sel_hi:[0,1]
	v_pk_mul_f32 v[32:33], v[32:33], v[36:37]
	v_pk_mul_f32 v[38:39], v[50:51], v[42:43] op_sel_hi:[0,1]
	v_pk_mul_f32 v[34:35], v[34:35], v[38:39]
	v_cvt_pk_bf16_f32 v42, v32, v33
	v_mad_i64_i32 v[32:33], s[18:19], v69, s9, v[112:113]
	v_cvt_pk_bf16_f32 v43, v34, v35
	v_lshl_add_u64 v[32:33], v[32:33], 0, v[114:115]
	global_store_dwordx4 v[32:33], v[40:43], off
	v_fmamk_f32 v32, v237, 0x3a800000, v194
	v_cmp_gt_f32_e32 vcc, s2, v32
	v_mul_f32_e32 v33, 0x4b800000, v32
	s_nop 0
	v_cndmask_b32_e32 v32, v32, v33, vcc
	v_rsq_f32_e32 v32, v32
	s_nop 0
	v_mul_f32_e32 v33, 0x45800000, v32
	v_cndmask_b32_e32 v33, v32, v33, vcc
	v_mul_f32_e32 v32, 0xbfb8aa3b, v33
	v_pk_mul_f32 v[38:39], v[28:29], v[32:33] op_sel_hi:[1,0]
	v_mul_f32_e32 v34, v33, v33
	v_pk_mul_f32 v[36:37], v[30:31], v[32:33] op_sel_hi:[1,0]
	v_exp_f32_e32 v33, v38
	s_nop 0
	v_add_f32_e32 v33, 1.0, v33
	v_rcp_f32_e32 v38, v33
	v_exp_f32_e32 v33, v39
	s_nop 0
	v_add_f32_e32 v33, 1.0, v33
	v_rcp_f32_e32 v39, v33
	v_exp_f32_e32 v33, v36
	v_pk_mul_f32 v[28:29], v[34:35], v[38:39] op_sel_hi:[0,1]
	v_add_f32_e32 v33, 1.0, v33
	v_rcp_f32_e32 v36, v33
	v_exp_f32_e32 v33, v37
	v_pk_mul_f32 v[24:25], v[24:25], v[28:29]
	v_add_f32_e32 v33, 1.0, v33
	v_rcp_f32_e32 v37, v33
	v_cvt_pk_bf16_f32 v28, v25, s0
	v_cvt_pk_bf16_f32 v24, v24, s0
	v_pk_mul_f32 v[30:31], v[34:35], v[36:37] op_sel_hi:[0,1]
	v_pk_mul_f32 v[26:27], v[26:27], v[30:31]
	s_nop 0
	v_cvt_pk_bf16_f32 v25, v26, v27
	v_lshlrev_b32_e32 v26, 16, v28
	v_pk_mul_f32 v[28:29], v[20:21], v[32:33] op_sel_hi:[1,0]
	v_or_b32_sdwa v24, v26, v24 dst_sel:DWORD dst_unused:UNUSED_PAD src0_sel:DWORD src1_sel:WORD_0
	v_pk_mul_f32 v[26:27], v[22:23], v[32:33] op_sel_hi:[1,0]
	v_exp_f32_e32 v28, v28
	v_exp_f32_e32 v29, v29
	v_exp_f32_e32 v26, v26
	v_exp_f32_e32 v27, v27
	v_add_f32_e32 v28, 1.0, v28
	v_add_f32_e32 v29, 1.0, v29
	v_rcp_f32_e32 v28, v28
	v_rcp_f32_e32 v29, v29
	v_add_f32_e32 v26, 1.0, v26
	v_add_f32_e32 v27, 1.0, v27
	v_rcp_f32_e32 v26, v26
	v_rcp_f32_e32 v27, v27
	v_pk_mul_f32 v[20:21], v[34:35], v[28:29] op_sel_hi:[0,1]
	v_pk_mul_f32 v[16:17], v[16:17], v[20:21]
	v_pk_mul_f32 v[22:23], v[34:35], v[26:27] op_sel_hi:[0,1]
	v_pk_mul_f32 v[18:19], v[18:19], v[22:23]
	v_cvt_pk_bf16_f32 v26, v16, v17
	v_mad_i64_i32 v[16:17], s[18:19], v66, s9, v[112:113]
	v_cvt_pk_bf16_f32 v27, v18, v19
	v_lshl_add_u64 v[16:17], v[16:17], 0, v[114:115]
	global_store_dwordx4 v[16:17], v[24:27], off
	v_fmamk_f32 v16, v238, 0x3a800000, v194
	v_cmp_gt_f32_e32 vcc, s2, v16
	v_mul_f32_e32 v17, 0x4b800000, v16
	s_nop 0
	v_cndmask_b32_e32 v16, v16, v17, vcc
	v_rsq_f32_e32 v16, v16
	s_nop 0
	v_mul_f32_e32 v17, 0x45800000, v16
	v_cndmask_b32_e32 v17, v16, v17, vcc
	v_mul_f32_e32 v16, 0xbfb8aa3b, v17
	v_pk_mul_f32 v[22:23], v[12:13], v[16:17] op_sel_hi:[1,0]
	v_mul_f32_e32 v18, v17, v17
	v_pk_mul_f32 v[20:21], v[14:15], v[16:17] op_sel_hi:[1,0]
	v_exp_f32_e32 v17, v22
	s_and_b64 vcc, exec, s[0:1]
	v_add_f32_e32 v17, 1.0, v17
	v_rcp_f32_e32 v22, v17
	v_exp_f32_e32 v17, v23
	s_nop 0
	v_add_f32_e32 v17, 1.0, v17
	v_rcp_f32_e32 v23, v17
	v_exp_f32_e32 v17, v20
	v_pk_mul_f32 v[12:13], v[18:19], v[22:23] op_sel_hi:[0,1]
	v_add_f32_e32 v17, 1.0, v17
	v_rcp_f32_e32 v20, v17
	v_exp_f32_e32 v17, v21
	v_pk_mul_f32 v[8:9], v[8:9], v[12:13]
	v_add_f32_e32 v17, 1.0, v17
	v_rcp_f32_e32 v21, v17
	v_cvt_pk_bf16_f32 v12, v9, s0
	v_cvt_pk_bf16_f32 v8, v8, s0
	v_pk_mul_f32 v[14:15], v[18:19], v[20:21] op_sel_hi:[0,1]
	v_pk_mul_f32 v[10:11], v[10:11], v[14:15]
	s_nop 0
	v_cvt_pk_bf16_f32 v9, v10, v11
	v_lshlrev_b32_e32 v10, 16, v12
	v_pk_mul_f32 v[12:13], v[4:5], v[16:17] op_sel_hi:[1,0]
	v_or_b32_sdwa v8, v10, v8 dst_sel:DWORD dst_unused:UNUSED_PAD src0_sel:DWORD src1_sel:WORD_0
	v_pk_mul_f32 v[10:11], v[6:7], v[16:17] op_sel_hi:[1,0]
	v_exp_f32_e32 v12, v12
	v_exp_f32_e32 v13, v13
	v_exp_f32_e32 v10, v10
	v_exp_f32_e32 v11, v11
	v_add_f32_e32 v12, 1.0, v12
	v_add_f32_e32 v13, 1.0, v13
	v_rcp_f32_e32 v12, v12
	v_rcp_f32_e32 v13, v13
	v_add_f32_e32 v10, 1.0, v10
	v_add_f32_e32 v11, 1.0, v11
	v_rcp_f32_e32 v10, v10
	v_rcp_f32_e32 v11, v11
	v_pk_mul_f32 v[4:5], v[18:19], v[12:13] op_sel_hi:[0,1]
	v_pk_mul_f32 v[0:1], v[0:1], v[4:5]
	v_pk_mul_f32 v[6:7], v[18:19], v[10:11] op_sel_hi:[0,1]
	v_pk_mul_f32 v[2:3], v[2:3], v[6:7]
	v_cvt_pk_bf16_f32 v10, v0, v1
	v_mad_i64_i32 v[0:1], s[18:19], v64, s9, v[112:113]
	v_cvt_pk_bf16_f32 v11, v2, v3
	v_lshl_add_u64 v[0:1], v[0:1], 0, v[114:115]
	s_mov_b64 s[18:19], s[14:15]
	global_store_dwordx4 v[0:1], v[8:11], off
	s_cbranch_vccz .LBB0_2801
	s_waitcnt vmcnt(0)
	s_cmpk_gt_u32 s25, 0xff
	s_cbranch_scc1 .LBB0_2808
	s_barrier

.LBB0_3618:
	s_add_u32 s20, s18, 0x100
	s_addc_u32 s21, s19, 0
	s_add_i32 s45, 0, 0x10000
	v_add_u32_e32 v140, s45, v196
	ds_read_b128 v[128:131], v140
	ds_read_b128 v[132:135], v140 offset:1024
	ds_read_b128 v[136:139], v140 offset:2048
	ds_read_b128 v[140:143], v140 offset:3072
	s_cmp_eq_u32 s44, 40
	s_cselect_b32 s25, s5, s21
	s_cselect_b32 s24, s4, s20
	s_cselect_b32 s23, s7, s43
	s_cselect_b32 s22, s6, s33
	s_add_i32 m0, s30, 0xc000
	ds_read_b128 v[144:147], v198
	ds_read_b128 v[148:151], v198 offset:1024
	ds_read_b128 v[152:155], v198 offset:2048
	ds_read_b128 v[156:159], v198 offset:3072
	ds_read_b128 v[160:163], v198 offset:4096
	ds_read_b128 v[164:167], v198 offset:5120
	ds_read_b128 v[168:171], v198 offset:6144
	ds_read_b128 v[172:175], v198 offset:7168
	global_load_lds_dwordx4 v214, s[18:19]
	s_add_i32 m0, s30, 0xe000
	s_nop 0
	global_load_lds_dwordx4 v212, s[18:19]
	s_waitcnt lgkmcnt(8)
	s_barrier
	s_waitcnt lgkmcnt(0)
	s_setprio 1
	s_waitcnt lgkmcnt(0)
	v_mfma_f32_16x16x32_bf16 v[124:127], v[128:131], v[144:147], v[124:127]
	v_mfma_f32_16x16x32_bf16 v[120:123], v[136:139], v[144:147], v[120:123]
	v_mfma_f32_16x16x32_bf16 v[108:111], v[128:131], v[152:155], v[108:111]
	v_mfma_f32_16x16x32_bf16 v[104:107], v[136:139], v[152:155], v[104:107]
	v_mfma_f32_16x16x32_bf16 v[92:95], v[128:131], v[160:163], v[92:95]
	v_mfma_f32_16x16x32_bf16 v[88:91], v[136:139], v[160:163], v[88:91]
	v_mfma_f32_16x16x32_bf16 v[76:79], v[128:131], v[168:171], v[76:79]
	v_mfma_f32_16x16x32_bf16 v[72:75], v[136:139], v[168:171], v[72:75]
	v_mfma_f32_16x16x32_bf16 v[124:127], v[132:135], v[148:151], v[124:127]
	v_mfma_f32_16x16x32_bf16 v[120:123], v[140:143], v[148:151], v[120:123]
	v_mfma_f32_16x16x32_bf16 v[108:111], v[132:135], v[156:159], v[108:111]
	v_mfma_f32_16x16x32_bf16 v[104:107], v[140:143], v[156:159], v[104:107]
	v_mfma_f32_16x16x32_bf16 v[92:95], v[132:135], v[164:167], v[92:95]
	v_mfma_f32_16x16x32_bf16 v[88:91], v[140:143], v[164:167], v[88:91]
	v_mfma_f32_16x16x32_bf16 v[76:79], v[132:135], v[172:175], v[76:79]
	v_mfma_f32_16x16x32_bf16 v[72:75], v[140:143], v[172:175], v[72:75]
	s_setprio 0
	s_barrier
	s_add_i32 s46, 0, 0x14000
	s_add_i32 s18, s45, s29
	v_add_u32_e32 v188, s46, v196
	s_mov_b32 m0, s18
	ds_read_b128 v[176:179], v188
	ds_read_b128 v[180:183], v188 offset:1024
	ds_read_b128 v[184:187], v188 offset:2048
	ds_read_b128 v[188:191], v188 offset:3072
	global_load_lds_dwordx4 v192, s[22:23]
	s_add_i32 m0, s18, 0x2000
	s_nop 0
	global_load_lds_dwordx4 v210, s[22:23]
	s_barrier
	s_waitcnt lgkmcnt(0)
	s_setprio 1
	s_waitcnt lgkmcnt(0)
	v_mfma_f32_16x16x32_bf16 v[116:119], v[176:179], v[144:147], v[116:119]
	v_mfma_f32_16x16x32_bf16 v[112:115], v[184:187], v[144:147], v[112:115]
	v_mfma_f32_16x16x32_bf16 v[100:103], v[176:179], v[152:155], v[100:103]
	v_mfma_f32_16x16x32_bf16 v[96:99], v[184:187], v[152:155], v[96:99]
	v_mfma_f32_16x16x32_bf16 v[84:87], v[176:179], v[160:163], v[84:87]
	v_mfma_f32_16x16x32_bf16 v[80:83], v[184:187], v[160:163], v[80:83]
	v_mfma_f32_16x16x32_bf16 v[68:71], v[176:179], v[168:171], v[68:71]
	v_mfma_f32_16x16x32_bf16 v[64:67], v[184:187], v[168:171], v[64:67]
	v_mfma_f32_16x16x32_bf16 v[116:119], v[180:183], v[148:151], v[116:119]
	v_mfma_f32_16x16x32_bf16 v[112:115], v[188:191], v[148:151], v[112:115]
	v_mfma_f32_16x16x32_bf16 v[100:103], v[180:183], v[156:159], v[100:103]
	v_mfma_f32_16x16x32_bf16 v[96:99], v[188:191], v[156:159], v[96:99]
	v_mfma_f32_16x16x32_bf16 v[84:87], v[180:183], v[164:167], v[84:87]
	v_mfma_f32_16x16x32_bf16 v[80:83], v[188:191], v[164:167], v[80:83]
	v_mfma_f32_16x16x32_bf16 v[68:71], v[180:183], v[172:175], v[68:71]
	v_mfma_f32_16x16x32_bf16 v[64:67], v[188:191], v[172:175], v[64:67]
	s_setprio 0
	s_mov_b32 m0, s30
	s_add_u32 vcc_lo, s24, 0x80
	s_addc_u32 vcc_hi, s25, 0
	s_barrier
	ds_read_b128 v[144:147], v198 offset:16384
	ds_read_b128 v[148:151], v198 offset:17408
	ds_read_b128 v[152:155], v198 offset:18432
	ds_read_b128 v[156:159], v198 offset:19456
	ds_read_b128 v[160:163], v198 offset:20480
	ds_read_b128 v[164:167], v198 offset:21504
	ds_read_b128 v[168:171], v198 offset:22528
	ds_read_b128 v[172:175], v198 offset:23552
	global_load_lds_dwordx4 v206, s[24:25]
	s_mov_b32 m0, s31
	s_nop 0
	global_load_lds_dwordx4 v208, s[24:25]
	s_barrier
	s_waitcnt lgkmcnt(0)
	s_setprio 1
	s_waitcnt lgkmcnt(0)
	v_mfma_f32_16x16x32_bf16 v[60:63], v[128:131], v[144:147], v[60:63]
	v_mfma_f32_16x16x32_bf16 v[56:59], v[136:139], v[144:147], v[56:59]
	v_mfma_f32_16x16x32_bf16 v[44:47], v[128:131], v[152:155], v[44:47]
	v_mfma_f32_16x16x32_bf16 v[40:43], v[136:139], v[152:155], v[40:43]
	v_mfma_f32_16x16x32_bf16 v[28:31], v[128:131], v[160:163], v[28:31]
	v_mfma_f32_16x16x32_bf16 v[24:27], v[136:139], v[160:163], v[24:27]
	v_mfma_f32_16x16x32_bf16 v[12:15], v[128:131], v[168:171], v[12:15]
	v_mfma_f32_16x16x32_bf16 v[8:11], v[136:139], v[168:171], v[8:11]
	v_mfma_f32_16x16x32_bf16 v[60:63], v[132:135], v[148:151], v[60:63]
	v_mfma_f32_16x16x32_bf16 v[56:59], v[140:143], v[148:151], v[56:59]
	v_mfma_f32_16x16x32_bf16 v[44:47], v[132:135], v[156:159], v[44:47]
	v_mfma_f32_16x16x32_bf16 v[40:43], v[140:143], v[156:159], v[40:43]
	v_mfma_f32_16x16x32_bf16 v[28:31], v[132:135], v[164:167], v[28:31]
	v_mfma_f32_16x16x32_bf16 v[24:27], v[140:143], v[164:167], v[24:27]
	v_mfma_f32_16x16x32_bf16 v[12:15], v[132:135], v[172:175], v[12:15]
	v_mfma_f32_16x16x32_bf16 v[8:11], v[140:143], v[172:175], v[8:11]
	s_setprio 0
	s_barrier
	s_add_u32 s18, s22, 0xb0000
	s_addc_u32 s19, s23, 0
	s_add_i32 s45, s46, s29
	s_mov_b32 m0, s45
	s_nop 0
	global_load_lds_dwordx4 v192, s[18:19]
	s_add_i32 m0, s45, 0x2000
	s_nop 0
	global_load_lds_dwordx4 v210, s[18:19]
	s_waitcnt vmcnt(6)
	s_barrier
	s_setprio 1
	v_mfma_f32_16x16x32_bf16 v[52:55], v[176:179], v[144:147], v[52:55]
	v_mfma_f32_16x16x32_bf16 v[48:51], v[184:187], v[144:147], v[48:51]
	v_mfma_f32_16x16x32_bf16 v[36:39], v[176:179], v[152:155], v[36:39]
	v_mfma_f32_16x16x32_bf16 v[32:35], v[184:187], v[152:155], v[32:35]
	v_mfma_f32_16x16x32_bf16 v[20:23], v[176:179], v[160:163], v[20:23]
	v_mfma_f32_16x16x32_bf16 v[16:19], v[184:187], v[160:163], v[16:19]
	v_mfma_f32_16x16x32_bf16 v[4:7], v[176:179], v[168:171], v[4:7]
	v_mfma_f32_16x16x32_bf16 v[0:3], v[184:187], v[168:171], v[0:3]
	v_mfma_f32_16x16x32_bf16 v[52:55], v[180:183], v[148:151], v[52:55]
	v_mfma_f32_16x16x32_bf16 v[48:51], v[188:191], v[148:151], v[48:51]
	v_mfma_f32_16x16x32_bf16 v[36:39], v[180:183], v[156:159], v[36:39]
	v_mfma_f32_16x16x32_bf16 v[32:35], v[188:191], v[156:159], v[32:35]
	v_mfma_f32_16x16x32_bf16 v[20:23], v[180:183], v[164:167], v[20:23]
	v_mfma_f32_16x16x32_bf16 v[16:19], v[188:191], v[164:167], v[16:19]
	v_mfma_f32_16x16x32_bf16 v[4:7], v[180:183], v[172:175], v[4:7]
	v_mfma_f32_16x16x32_bf16 v[0:3], v[188:191], v[172:175], v[0:3]
	s_setprio 0
	s_add_i32 s45, 0, 0x18000
	v_add_u32_e32 v140, s45, v196
	s_barrier
	ds_read_b128 v[128:131], v140
	ds_read_b128 v[132:135], v140 offset:1024
	ds_read_b128 v[136:139], v140 offset:2048
	ds_read_b128 v[140:143], v140 offset:3072
	s_add_u32 s18, s24, 0xb0000
	s_addc_u32 s19, s25, 0
	s_mov_b32 m0, s34
	ds_read_b128 v[144:147], v198 offset:32768
	ds_read_b128 v[148:151], v198 offset:33792
	ds_read_b128 v[152:155], v198 offset:34816
	ds_read_b128 v[156:159], v198 offset:35840
	ds_read_b128 v[160:163], v198 offset:36864
	ds_read_b128 v[164:167], v198 offset:37888
	ds_read_b128 v[168:171], v198 offset:38912
	ds_read_b128 v[172:175], v198 offset:39936
	global_load_lds_dwordx4 v206, s[18:19]
	s_mov_b32 m0, s35
	s_nop 0
	global_load_lds_dwordx4 v208, s[18:19]
	s_waitcnt lgkmcnt(8)
	s_barrier
	s_waitcnt lgkmcnt(0)
	s_setprio 1
	s_waitcnt lgkmcnt(0)
	v_mfma_f32_16x16x32_bf16 v[124:127], v[128:131], v[144:147], v[124:127]
	v_mfma_f32_16x16x32_bf16 v[120:123], v[136:139], v[144:147], v[120:123]
	v_mfma_f32_16x16x32_bf16 v[108:111], v[128:131], v[152:155], v[108:111]
	v_mfma_f32_16x16x32_bf16 v[104:107], v[136:139], v[152:155], v[104:107]
	v_mfma_f32_16x16x32_bf16 v[92:95], v[128:131], v[160:163], v[92:95]
	v_mfma_f32_16x16x32_bf16 v[88:91], v[136:139], v[160:163], v[88:91]
	v_mfma_f32_16x16x32_bf16 v[76:79], v[128:131], v[168:171], v[76:79]
	v_mfma_f32_16x16x32_bf16 v[72:75], v[136:139], v[168:171], v[72:75]
	v_mfma_f32_16x16x32_bf16 v[124:127], v[132:135], v[148:151], v[124:127]
	v_mfma_f32_16x16x32_bf16 v[120:123], v[140:143], v[148:151], v[120:123]
	v_mfma_f32_16x16x32_bf16 v[108:111], v[132:135], v[156:159], v[108:111]
	v_mfma_f32_16x16x32_bf16 v[104:107], v[140:143], v[156:159], v[104:107]
	v_mfma_f32_16x16x32_bf16 v[92:95], v[132:135], v[164:167], v[92:95]
	v_mfma_f32_16x16x32_bf16 v[88:91], v[140:143], v[164:167], v[88:91]
	v_mfma_f32_16x16x32_bf16 v[76:79], v[132:135], v[172:175], v[76:79]
	v_mfma_f32_16x16x32_bf16 v[72:75], v[140:143], v[172:175], v[72:75]
	s_setprio 0
	s_barrier
	s_add_i32 s24, 0, 0x1c000
	s_add_i32 s18, s45, s29
	v_add_u32_e32 v188, s24, v196
	s_add_u32 s100, s22, 0x80
	s_addc_u32 s101, s23, 0
	s_mov_b32 m0, s18
	ds_read_b128 v[176:179], v188
	ds_read_b128 v[180:183], v188 offset:1024
	ds_read_b128 v[184:187], v188 offset:2048
	ds_read_b128 v[188:191], v188 offset:3072
	global_load_lds_dwordx4 v192, s[100:101]
	s_add_i32 m0, s18, 0x2000
	s_nop 0
	global_load_lds_dwordx4 v210, s[100:101]
	s_barrier
	s_waitcnt lgkmcnt(0)
	s_setprio 1
	s_waitcnt lgkmcnt(0)
	v_mfma_f32_16x16x32_bf16 v[116:119], v[176:179], v[144:147], v[116:119]
	v_mfma_f32_16x16x32_bf16 v[112:115], v[184:187], v[144:147], v[112:115]
	v_mfma_f32_16x16x32_bf16 v[100:103], v[176:179], v[152:155], v[100:103]
	v_mfma_f32_16x16x32_bf16 v[96:99], v[184:187], v[152:155], v[96:99]
	v_mfma_f32_16x16x32_bf16 v[84:87], v[176:179], v[160:163], v[84:87]
	v_mfma_f32_16x16x32_bf16 v[80:83], v[184:187], v[160:163], v[80:83]
	v_mfma_f32_16x16x32_bf16 v[68:71], v[176:179], v[168:171], v[68:71]
	v_mfma_f32_16x16x32_bf16 v[64:67], v[184:187], v[168:171], v[64:67]
	v_mfma_f32_16x16x32_bf16 v[116:119], v[180:183], v[148:151], v[116:119]
	v_mfma_f32_16x16x32_bf16 v[112:115], v[188:191], v[148:151], v[112:115]
	v_mfma_f32_16x16x32_bf16 v[100:103], v[180:183], v[156:159], v[100:103]
	v_mfma_f32_16x16x32_bf16 v[96:99], v[188:191], v[156:159], v[96:99]
	v_mfma_f32_16x16x32_bf16 v[84:87], v[180:183], v[164:167], v[84:87]
	v_mfma_f32_16x16x32_bf16 v[80:83], v[188:191], v[164:167], v[80:83]
	v_mfma_f32_16x16x32_bf16 v[68:71], v[180:183], v[172:175], v[68:71]
	v_mfma_f32_16x16x32_bf16 v[64:67], v[188:191], v[172:175], v[64:67]
	s_setprio 0
	s_mov_b32 m0, s36
	s_barrier
	ds_read_b128 v[144:147], v198 offset:49152
	ds_read_b128 v[148:151], v198 offset:50176
	ds_read_b128 v[152:155], v198 offset:51200
	ds_read_b128 v[156:159], v198 offset:52224
	ds_read_b128 v[160:163], v198 offset:53248
	ds_read_b128 v[164:167], v198 offset:54272
	ds_read_b128 v[168:171], v198 offset:55296
	ds_read_b128 v[172:175], v198 offset:56320
	global_load_lds_dwordx4 v206, vcc
	s_mov_b32 m0, s37
	s_nop 0
	global_load_lds_dwordx4 v208, vcc
	s_barrier
	s_waitcnt lgkmcnt(0)
	s_setprio 1
	s_waitcnt lgkmcnt(0)
	v_mfma_f32_16x16x32_bf16 v[60:63], v[128:131], v[144:147], v[60:63]
	v_mfma_f32_16x16x32_bf16 v[56:59], v[136:139], v[144:147], v[56:59]
	v_mfma_f32_16x16x32_bf16 v[44:47], v[128:131], v[152:155], v[44:47]
	v_mfma_f32_16x16x32_bf16 v[40:43], v[136:139], v[152:155], v[40:43]
	v_mfma_f32_16x16x32_bf16 v[28:31], v[128:131], v[160:163], v[28:31]
	v_mfma_f32_16x16x32_bf16 v[24:27], v[136:139], v[160:163], v[24:27]
	v_mfma_f32_16x16x32_bf16 v[12:15], v[128:131], v[168:171], v[12:15]
	v_mfma_f32_16x16x32_bf16 v[8:11], v[136:139], v[168:171], v[8:11]
	v_mfma_f32_16x16x32_bf16 v[60:63], v[132:135], v[148:151], v[60:63]
	v_mfma_f32_16x16x32_bf16 v[56:59], v[140:143], v[148:151], v[56:59]
	v_mfma_f32_16x16x32_bf16 v[44:47], v[132:135], v[156:159], v[44:47]
	v_mfma_f32_16x16x32_bf16 v[40:43], v[140:143], v[156:159], v[40:43]
	v_mfma_f32_16x16x32_bf16 v[28:31], v[132:135], v[164:167], v[28:31]
	v_mfma_f32_16x16x32_bf16 v[24:27], v[140:143], v[164:167], v[24:27]
	v_mfma_f32_16x16x32_bf16 v[12:15], v[132:135], v[172:175], v[12:15]
	v_mfma_f32_16x16x32_bf16 v[8:11], v[140:143], v[172:175], v[8:11]
	s_setprio 0
	s_barrier
	s_add_u32 s18, s22, 0xb0080
	s_addc_u32 s19, s23, 0
	s_add_i32 s22, s24, s29
	s_mov_b32 m0, s22
	s_nop 0
	global_load_lds_dwordx4 v192, s[18:19]
	s_add_i32 m0, s22, 0x2000
	s_nop 0
	global_load_lds_dwordx4 v210, s[18:19]
	s_waitcnt vmcnt(6)
	s_barrier
	s_setprio 1
	v_mfma_f32_16x16x32_bf16 v[52:55], v[176:179], v[144:147], v[52:55]
	v_mfma_f32_16x16x32_bf16 v[48:51], v[184:187], v[144:147], v[48:51]
	v_mfma_f32_16x16x32_bf16 v[36:39], v[176:179], v[152:155], v[36:39]
	v_mfma_f32_16x16x32_bf16 v[32:35], v[184:187], v[152:155], v[32:35]
	v_mfma_f32_16x16x32_bf16 v[20:23], v[176:179], v[160:163], v[20:23]
	v_mfma_f32_16x16x32_bf16 v[16:19], v[184:187], v[160:163], v[16:19]
	v_mfma_f32_16x16x32_bf16 v[4:7], v[176:179], v[168:171], v[4:7]
	v_mfma_f32_16x16x32_bf16 v[0:3], v[184:187], v[168:171], v[0:3]
	v_mfma_f32_16x16x32_bf16 v[52:55], v[180:183], v[148:151], v[52:55]
	v_mfma_f32_16x16x32_bf16 v[48:51], v[188:191], v[148:151], v[48:51]
	v_mfma_f32_16x16x32_bf16 v[36:39], v[180:183], v[156:159], v[36:39]
	v_mfma_f32_16x16x32_bf16 v[32:35], v[188:191], v[156:159], v[32:35]
	v_mfma_f32_16x16x32_bf16 v[20:23], v[180:183], v[164:167], v[20:23]
	v_mfma_f32_16x16x32_bf16 v[16:19], v[188:191], v[164:167], v[16:19]
	v_mfma_f32_16x16x32_bf16 v[4:7], v[180:183], v[172:175], v[4:7]
	v_mfma_f32_16x16x32_bf16 v[0:3], v[188:191], v[172:175], v[0:3]
	s_setprio 0
	s_add_i32 s44, s44, 2
	s_add_u32 s33, s33, 0x100
	s_addc_u32 s43, s43, 0
	s_cmp_gt_u32 s44, 41
	s_mov_b64 s[18:19], s[20:21]
	s_barrier
	s_cbranch_scc0 .LBB0_3618
	v_mov_b32_e32 v128, v252
	s_lshl_b32 s19, s42, 8
	v_readfirstlane_b32 s18, v128
	s_ashr_i32 s20, s18, 2
	s_andn2_b32 s20, s20, 63
	s_lshr_b32 s18, s18, 1
	s_add_i32 s20, s20, s19
	s_and_b32 s18, s18, 0x60
	s_lshl_b32 s19, s41, 8
	v_and_or_b32 v218, v128, 15, s20
	v_lshrrev_b32_e32 v128, 1, v128
	s_or_b32 s18, s18, s19
	v_and_b32_e32 v129, 64, v195
	v_and_or_b32 v216, v128, 24, s18
	v_xor_b32_e32 v128, 16, v195
	v_add_u32_e32 v129, 64, v129
	v_cmp_lt_i32_e32 vcc, v128, v129
	v_ashrrev_i32_e32 v219, 31, v218
	v_ashrrev_i32_e32 v217, 31, v216
	v_cndmask_b32_e32 v128, v195, v128, vcc
	v_lshlrev_b32_e32 v200, 2, v128
	v_xor_b32_e32 v128, 32, v195
	v_cmp_lt_i32_e32 vcc, v128, v129
	v_or_b32_e32 v220, 0x80, v216
	v_ashrrev_i32_e32 v221, 31, v220
	v_cndmask_b32_e32 v128, v195, v128, vcc
	v_lshlrev_b32_e32 v199, 2, v128
	v_lshlrev_b64 v[128:129], 10, v[218:219]
	v_lshl_add_u64 v[130:131], v[128:129], 0, v[216:217]
	v_lshlrev_b64 v[130:131], 1, v[130:131]
	v_lshl_add_u64 v[246:247], s[10:11], 0, v[130:131]
	v_lshl_add_u64 v[250:251], s[12:13], 0, v[130:131]
	global_load_dwordx4 v[188:191], v[246:247], off
	global_load_dwordx4 v[180:183], v[246:247], off offset:256
	global_load_dwordx4 v[184:187], v[250:251], off
	v_or_b32_e32 v242, 16, v218
	v_lshl_add_u64 v[128:129], v[128:129], 0, v[220:221]
	v_ashrrev_i32_e32 v243, 31, v242
	v_lshl_add_u64 v[248:249], v[128:129], 1, s[12:13]
	v_lshlrev_b64 v[128:129], 10, v[242:243]
	v_or_b32_e32 v234, 32, v218
	v_lshl_add_u64 v[130:131], v[128:129], 0, v[216:217]
	v_lshl_add_u64 v[128:129], v[128:129], 0, v[220:221]
	v_ashrrev_i32_e32 v235, 31, v234
	v_lshlrev_b64 v[130:131], 1, v[130:131]
	v_lshl_add_u64 v[240:241], v[128:129], 1, s[12:13]
	v_lshlrev_b64 v[128:129], 10, v[234:235]
	v_or_b32_e32 v226, 48, v218
	v_lshl_add_u64 v[238:239], s[10:11], 0, v[130:131]
	v_lshl_add_u64 v[244:245], s[12:13], 0, v[130:131]
	v_lshl_add_u64 v[130:131], v[128:129], 0, v[216:217]
	v_lshl_add_u64 v[128:129], v[128:129], 0, v[220:221]
	v_ashrrev_i32_e32 v227, 31, v226
	v_lshlrev_b64 v[130:131], 1, v[130:131]
	v_lshl_add_u64 v[232:233], v[128:129], 1, s[12:13]
	v_lshlrev_b64 v[128:129], 10, v[226:227]
	v_lshl_add_u64 v[228:229], s[10:11], 0, v[130:131]
	v_lshl_add_u64 v[236:237], s[12:13], 0, v[130:131]
	v_lshl_add_u64 v[130:131], v[128:129], 0, v[216:217]
	v_lshlrev_b64 v[130:131], 1, v[130:131]
	v_lshl_add_u64 v[132:133], v[128:129], 0, v[220:221]
	v_lshl_add_u64 v[222:223], s[10:11], 0, v[130:131]
	v_lshl_add_u64 v[230:231], s[12:13], 0, v[130:131]
	v_lshl_add_u64 v[224:225], v[132:133], 1, s[12:13]
	global_load_dwordx4 v[176:179], v[248:249], off
	global_load_dwordx4 v[172:175], v[238:239], off
	global_load_dwordx4 v[164:167], v[238:239], off offset:256
	global_load_dwordx4 v[168:171], v[244:245], off
	global_load_dwordx4 v[160:163], v[240:241], off
	global_load_dwordx4 v[156:159], v[228:229], off
	global_load_dwordx4 v[132:135], v[224:225], off
	global_load_dwordx4 v[152:155], v[236:237], off
	global_load_dwordx4 v[144:147], v[232:233], off
	global_load_dwordx4 v[148:151], v[228:229], off offset:256
	global_load_dwordx4 v[136:139], v[230:231], off
	global_load_dwordx4 v[140:143], v[222:223], off
	global_load_dwordx4 v[128:131], v[222:223], off offset:256
	v_cmp_gt_u32_e32 vcc, 16, v195
	s_waitcnt vmcnt(0)
	v_lshlrev_b32_e32 v202, 16, v188
	v_and_b32_e32 v203, 0xffff0000, v188
	v_lshlrev_b32_e32 v204, 16, v184
	v_and_b32_e32 v205, 0xffff0000, v184
	v_lshlrev_b32_e32 v188, 16, v189
	v_and_b32_e32 v189, 0xffff0000, v189
	v_lshlrev_b32_e32 v184, 16, v185
	v_and_b32_e32 v185, 0xffff0000, v185
	v_pk_add_f32 v[202:203], v[202:203], v[204:205]
	v_pk_add_f32 v[184:185], v[188:189], v[184:185]
	v_pk_fma_f32 v[188:189], v[124:125], 0.5, v[202:203] op_sel_hi:[1,0,1]
	v_pk_fma_f32 v[184:185], v[126:127], 0.5, v[184:185] op_sel_hi:[1,0,1]
	v_lshlrev_b32_e32 v124, 16, v190
	v_and_b32_e32 v125, 0xffff0000, v190
	v_lshlrev_b32_e32 v126, 16, v186
	v_and_b32_e32 v127, 0xffff0000, v186
	v_pk_add_f32 v[124:125], v[124:125], v[126:127]
	v_lshlrev_b32_e32 v126, 16, v191
	v_and_b32_e32 v127, 0xffff0000, v191
	v_lshlrev_b32_e32 v186, 16, v187
	v_and_b32_e32 v187, 0xffff0000, v187
	v_pk_add_f32 v[126:127], v[126:127], v[186:187]
	v_pk_fma_f32 v[190:191], v[120:121], 0.5, v[124:125] op_sel_hi:[1,0,1]
	v_cvt_pk_bf16_f32 v120, v188, v189
	v_pk_fma_f32 v[186:187], v[122:123], 0.5, v[126:127] op_sel_hi:[1,0,1]
	v_and_b32_e32 v123, 0xffff0000, v120
	v_lshlrev_b32_e32 v122, 16, v120
	v_pk_add_f32 v[122:123], v[188:189], v[122:123] neg_lo:[0,1] neg_hi:[0,1]
	v_cvt_pk_bf16_f32 v121, v184, v185
	v_cvt_pk_bf16_f32 v124, v122, v123
	v_and_b32_e32 v123, 0xffff0000, v121
	v_lshlrev_b32_e32 v122, 16, v121
	v_pk_add_f32 v[122:123], v[184:185], v[122:123] neg_lo:[0,1] neg_hi:[0,1]
	s_nop 0
	v_cvt_pk_bf16_f32 v125, v122, v123
	v_cvt_pk_bf16_f32 v122, v190, v191
	v_cvt_pk_bf16_f32 v123, v186, v187
	v_and_b32_e32 v127, 0xffff0000, v122
	v_lshlrev_b32_e32 v126, 16, v122
	v_and_b32_e32 v203, 0xffff0000, v123
	v_lshlrev_b32_e32 v202, 16, v123
	v_pk_add_f32 v[126:127], v[190:191], v[126:127] neg_lo:[0,1] neg_hi:[0,1]
	v_pk_add_f32 v[202:203], v[186:187], v[202:203] neg_lo:[0,1] neg_hi:[0,1]
	v_cvt_pk_bf16_f32 v126, v126, v127
	v_cvt_pk_bf16_f32 v127, v202, v203
	global_store_dwordx4 v[246:247], v[120:123], off
	global_store_dwordx4 v[250:251], v[124:127], off
	s_nop 0
	v_pk_mul_f32 v[122:123], v[190:191], v[190:191]
	v_pk_mul_f32 v[120:121], v[186:187], v[186:187]
	v_pk_fma_f32 v[122:123], v[188:189], v[188:189], v[122:123]
	v_pk_fma_f32 v[120:121], v[184:185], v[184:185], v[120:121]
	v_add_f32_e32 v122, v122, v123
	v_add_f32_e32 v120, v120, v122
	v_add_f32_e32 v120, v121, v120
	ds_bpermute_b32 v121, v200, v120
	s_waitcnt lgkmcnt(0)
	v_add_f32_e32 v122, v120, v121
	ds_bpermute_b32 v123, v199, v122
	v_lshl_add_u64 v[120:121], v[218:219], 2, s[16:17]
	s_and_saveexec_b64 s[18:19], vcc
	s_cbranch_execz .LBB0_3621
	s_waitcnt lgkmcnt(0)
	v_add_f32_e32 v122, v122, v123
	global_atomic_add_f32 v[120:121], v122, off

	.amdhsa_kernel _Z4mega6Params
		.amdhsa_group_segment_fixed_size 0
		.amdhsa_private_segment_fixed_size 0
		.amdhsa_kernarg_size 456
		.amdhsa_user_sgpr_count 2
		.amdhsa_user_sgpr_dispatch_ptr 0
		.amdhsa_user_sgpr_queue_ptr 0
		.amdhsa_user_sgpr_kernarg_segment_ptr 1
		.amdhsa_user_sgpr_dispatch_id 0
		.amdhsa_user_sgpr_kernarg_preload_length 0
		.amdhsa_user_sgpr_kernarg_preload_offset 0
		.amdhsa_user_sgpr_private_segment_size 0
		.amdhsa_uses_dynamic_stack 0
		.amdhsa_enable_private_segment 0
		.amdhsa_system_sgpr_workgroup_id_x 1
		.amdhsa_system_sgpr_workgroup_id_y 0
		.amdhsa_system_sgpr_workgroup_id_z 0
		.amdhsa_system_sgpr_workgroup_info 0
		.amdhsa_system_vgpr_workitem_id 2
		.amdhsa_next_free_vgpr 256
		.amdhsa_next_free_sgpr 102
		.amdhsa_accum_offset 256
		.amdhsa_reserve_vcc 1
		.amdhsa_float_round_mode_32 0
		.amdhsa_float_round_mode_16_64 0
		.amdhsa_float_denorm_mode_32 3
		.amdhsa_float_denorm_mode_16_64 3
		.amdhsa_dx10_clamp 1
		.amdhsa_ieee_mode 1
		.amdhsa_fp16_overflow 0
		.amdhsa_tg_split 0
		.amdhsa_exception_fp_ieee_invalid_op 0
		.amdhsa_exception_fp_denorm_src 0
		.amdhsa_exception_fp_ieee_div_zero 0
		.amdhsa_exception_fp_ieee_overflow 0
		.amdhsa_exception_fp_ieee_underflow 0
		.amdhsa_exception_fp_ieee_inexact 0
		.amdhsa_exception_int_div_zero 0
	.end_amdhsa_kernel

amdhsa.kernels:
  - .agpr_count:     0
    .args:
      - .offset:         0
        .size:           200
        .value_kind:     by_value
      - .offset:         200
        .size:           4
        .value_kind:     hidden_block_count_x
      - .offset:         204
        .size:           4
        .value_kind:     hidden_block_count_y
      - .offset:         208
        .size:           4
        .value_kind:     hidden_block_count_z
      - .offset:         212
        .size:           2
        .value_kind:     hidden_group_size_x
      - .offset:         214
        .size:           2
        .value_kind:     hidden_group_size_y
      - .offset:         216
        .size:           2
        .value_kind:     hidden_group_size_z
      - .offset:         218
        .size:           2
        .value_kind:     hidden_remainder_x
      - .offset:         220
        .size:           2
        .value_kind:     hidden_remainder_y
      - .offset:         222
        .size:           2
        .value_kind:     hidden_remainder_z
      - .offset:         240
        .size:           8
        .value_kind:     hidden_global_offset_x
      - .offset:         248
        .size:           8
        .value_kind:     hidden_global_offset_y
      - .offset:         256
        .size:           8
        .value_kind:     hidden_global_offset_z
      - .offset:         264
        .size:           2
        .value_kind:     hidden_grid_dims
      - .offset:         288
        .size:           8
        .value_kind:     hidden_multigrid_sync_arg
      - .offset:         320
        .size:           4
        .value_kind:     hidden_dynamic_lds_size
    .group_segment_fixed_size: 0
    .kernarg_segment_align: 8
    .kernarg_segment_size: 456
    .language:       OpenCL C
    .language_version:
      - 2
      - 0
    .max_flat_workgroup_size: 512
    .name:           _Z4mega6Params
    .private_segment_fixed_size: 0
    .sgpr_count:     108
    .sgpr_spill_count: 192
    .symbol:         _Z4mega6Params.kd
    .uniform_work_group_size: 1
    .uses_dynamic_stack: false
    .vgpr_count:     256
    .vgpr_spill_count: 0
    .wavefront_size: 64
